# combined version plus hand-written EpiAct SiLU section, deeper V-fragment read-ahead in cross-attention, LDS-DMA header staging
# baseline (speedup 1.0000x reference)
; #define PG8_GAS __attribute__((address_space(1)))
; __device__ __forceinline__ unsigned pk2_(float lo, float hi) { f32x2c_t v = {lo, hi}; bf16x2c_t b = __builtin_convertvector(v, bf16x2c_t); return __builtin_bit_cast(unsigned, b); }
; __device__ __forceinline__ float row_rstd(const float* parts, int r, int fq) {
;     const f32x4 p = *(const PG8_GAS f32x4*)(parts + (size_t)r * 16 + 4 * fq);
;     float s = (p[0] + p[1]) + (p[2] + p[3]);
;     s += __shfl_xor(s, 16); s += __shfl_xor(s, 32);
;     return rsqrtf(s * (1.0f / 1024.0f) + RMS_EPS);
; }
; __device__ __forceinline__ float silu_f(float x) { return x * __builtin_amdgcn_rcpf(1.0f + __builtin_amdgcn_exp2f(-1.4426950408889634f * x)); }
;     __device__ __forceinline__ void operator()(const f32x4 (&acc)[2][2][4][2], const Unit& u, int wr, int wc, int fr, int fq) const {
;         const int row0 = u.pm * BM + wr * 64 + fr, col0 = u.pn * 128 + wc * 32 + 8 * fq;
;         float rs8[2][4];
; #pragma unroll
;         for (int ai = 0; ai < 2; ++ai)
; #pragma unroll
;             for (int m = 0; m < 4; ++m) rs8[ai][m] = row_rstd(parts, row0 + ai * HALF + m * 16, fq);
; #pragma unroll
;         for (int ai = 0; ai < 2; ++ai)
; #pragma unroll
;             for (int m = 0; m < 4; ++m) {
;                 const int r = row0 + ai * HALF + m * 16; const float s = rs8[ai][m];
;                 float o[8];
; #pragma unroll
;                 for (int n = 0; n < 2; ++n)
; #pragma unroll
;                     for (int i = 0; i < 4; ++i) o[4 * n + i] = silu_f(acc[ai][0][m][n][i] * s) * (acc[ai][1][m][n][i] * s);
;                 u32x4 w; w.x = pk2_(o[0], o[1]); w.y = pk2_(o[2], o[3]); w.z = pk2_(o[4], o[5]); w.w = pk2_(o[6], o[7]);
;                 *(PG8_GAS u32x4*)(O + (size_t)r * 2816 + col0) = w;
.LBB0_697:
	s_lshl_b32 s6, s6, 8
	v_mov_b32_e32 v132, v252
	s_add_i32 s6, s6, s53
	s_mov_b32 s98, s53
	v_bfe_u32 v200, v132, 4, 2
	v_and_or_b32 v160, v132, 15, s6
	v_lshlrev_b32_e32 v132, 4, v200
	v_ashrrev_i32_e32 v161, 31, v160
	v_or_b32_e32 v156, 16, v160
	v_lshl_add_u64 v[190:191], s[80:81], 0, v[132:133]
	v_ashrrev_i32_e32 v157, 31, v156
	v_or_b32_e32 v152, 32, v160
	v_ashrrev_i32_e32 v153, 31, v152
	v_or_b32_e32 v148, 48, v160
	v_ashrrev_i32_e32 v149, 31, v148
	v_add_u32_e32 v146, 0x80, v160
	v_ashrrev_i32_e32 v147, 31, v146
	v_add_u32_e32 v144, 0x90, v160
	v_ashrrev_i32_e32 v145, 31, v144
	v_and_b32_e32 v140, 64, v165
	v_add_u32_e32 v147, 64, v140
	v_add_u32_e32 v142, 0xa0, v160
	v_add_u32_e32 v140, 0xb0, v160
	v_xor_b32_e32 v132, 16, v165
	v_cmp_lt_i32_e32 vcc, v132, v147
	v_xor_b32_e32 v145, 32, v165
	s_nop 0
	v_cndmask_b32_e32 v132, v165, v132, vcc
	v_lshlrev_b32_e32 v132, 2, v132
	v_cmp_lt_i32_e32 vcc, v145, v147
	v_mov_b64_e32 v[174:175], s[28:29]
	v_add_f32_e32 v240, v240, v241
	v_add_f32_e32 v242, v242, v243
	v_add_f32_e32 v244, v244, v245
	v_add_f32_e32 v246, v246, v247
	v_add_f32_e32 v240, v240, v242
	v_add_f32_e32 v244, v244, v246
	v_mov_b32_e32 v242, 0x358637bd
	s_nop 0
	v_add_f32_dpp v241, v240, v240 quad_perm:[1,0,3,2] row_mask:0xf bank_mask:0xf
	v_add_f32_dpp v245, v244, v244 quad_perm:[1,0,3,2] row_mask:0xf bank_mask:0xf
	v_and_b32_e32 v243, 60, v252
	v_lshl_add_u32 v243, v249, 7, v243
	v_add_f32_dpp v240, v241, v241 quad_perm:[2,3,0,1] row_mask:0xf bank_mask:0xf
	v_add_f32_dpp v244, v245, v245 quad_perm:[2,3,0,1] row_mask:0xf bank_mask:0xf
	v_add_u32_e32 v243, 0x21000, v243
	v_and_b32_e32 v246, 15, v252
	v_fmamk_f32 v240, v240, 0x3a800000, v242
	v_fmamk_f32 v244, v244, 0x3a800000, v242
	v_add_u32_e32 v246, s98, v246
	v_rsq_f32_e32 v240, v240
	v_rsq_f32_e32 v244, v244
	v_lshlrev_b32_e32 v246, 2, v246
	v_add_u32_e32 v246, 0x21000, v246
	ds_write_b32 v243, v240
	ds_write_b32 v243, v244 offset:64
	s_waitcnt lgkmcnt(0)
	s_barrier
	ds_read_b32 v166, v246
	ds_read_b32 v172, v246 offset:64
	ds_read_b32 v164, v246 offset:128
	ds_read_b32 v162, v246 offset:192
	ds_read_b32 v158, v246 offset:512
	ds_read_b32 v154, v246 offset:576
	ds_read_b32 v150, v246 offset:640
	ds_read_b32 v132, v246 offset:704
	s_waitcnt lgkmcnt(0)
	s_lshl_b32 s6, s60, 7
	v_lshl_or_b32 v141, v200, 3, s6
	v_or_b32_e32 v168, s54, v141
	v_ashrrev_i32_e32 v169, 31, v168
	v_lshlrev_b64 v[168:169], 1, v[168:169]
	v_mov_b64_e32 v[170:171], s[14:15]
	v_mul_f32_e32 v174, 0xbfb8aa3b, v166
	v_mul_f32_e32 v175, v166, v166
	v_pk_mul_f32 v[116:117], v[124:125], v[116:117]
	v_pk_mul_f32 v[118:119], v[126:127], v[118:119]
	v_pk_mul_f32 v[124:125], v[124:125], v[174:175] op_sel_hi:[1,0]
	v_pk_mul_f32 v[126:127], v[126:127], v[174:175] op_sel_hi:[1,0]
	v_exp_f32_e32 v124, v124
	v_exp_f32_e32 v125, v125
	v_exp_f32_e32 v126, v126
	v_exp_f32_e32 v127, v127
	v_pk_add_f32 v[124:125], v[124:125], 1.0 op_sel_hi:[1,0]
	v_pk_mul_f32 v[116:117], v[116:117], v[174:175] op_sel:[0,1] op_sel_hi:[1,1]
	v_pk_add_f32 v[126:127], v[126:127], 1.0 op_sel_hi:[1,0]
	v_rcp_f32_e32 v124, v124
	v_rcp_f32_e32 v125, v125
	v_pk_mul_f32 v[118:119], v[118:119], v[174:175] op_sel:[0,1] op_sel_hi:[1,1]
	v_rcp_f32_e32 v126, v126
	v_rcp_f32_e32 v127, v127
	v_pk_mul_f32 v[116:117], v[116:117], v[124:125]
	s_nop 0
	v_pk_mul_f32 v[118:119], v[118:119], v[126:127]
	v_pk_mul_f32 v[112:113], v[120:121], v[112:113]
	v_pk_mul_f32 v[114:115], v[122:123], v[114:115]
	v_pk_mul_f32 v[120:121], v[120:121], v[174:175] op_sel_hi:[1,0]
	v_pk_mul_f32 v[122:123], v[122:123], v[174:175] op_sel_hi:[1,0]
	v_exp_f32_e32 v120, v120
	v_exp_f32_e32 v121, v121
	v_exp_f32_e32 v122, v122
	v_exp_f32_e32 v123, v123
	v_pk_add_f32 v[120:121], v[120:121], 1.0 op_sel_hi:[1,0]
	v_pk_mul_f32 v[112:113], v[112:113], v[174:175] op_sel:[0,1] op_sel_hi:[1,1]
	v_pk_add_f32 v[122:123], v[122:123], 1.0 op_sel_hi:[1,0]
	v_rcp_f32_e32 v120, v120
	v_rcp_f32_e32 v121, v121
	v_pk_mul_f32 v[114:115], v[114:115], v[174:175] op_sel:[0,1] op_sel_hi:[1,1]
	v_rcp_f32_e32 v122, v122
	v_rcp_f32_e32 v123, v123
	v_pk_mul_f32 v[112:113], v[112:113], v[120:121]
	s_nop 0
	v_pk_mul_f32 v[114:115], v[114:115], v[122:123]
	v_cvt_pk_bf16_f32 v116, v116, v117
	v_cvt_pk_bf16_f32 v117, v118, v119
	v_cvt_pk_bf16_f32 v118, v112, v113
	v_cvt_pk_bf16_f32 v119, v114, v115
	v_mad_i64_i32 v[120:121], s[6:7], v160, s59, v[170:171]
	v_lshl_add_u64 v[120:121], v[120:121], 0, v[168:169]
	global_store_dwordx4 v[120:121], v[116:119], off
	v_mul_f32_e32 v174, 0xbfb8aa3b, v172
	v_mul_f32_e32 v175, v172, v172
	v_pk_mul_f32 v[100:101], v[108:109], v[100:101]
	v_pk_mul_f32 v[102:103], v[110:111], v[102:103]
	v_pk_mul_f32 v[108:109], v[108:109], v[174:175] op_sel_hi:[1,0]
	v_pk_mul_f32 v[110:111], v[110:111], v[174:175] op_sel_hi:[1,0]
	v_exp_f32_e32 v108, v108
	v_exp_f32_e32 v109, v109
	v_exp_f32_e32 v110, v110
	v_exp_f32_e32 v111, v111
	v_pk_add_f32 v[108:109], v[108:109], 1.0 op_sel_hi:[1,0]
	v_pk_mul_f32 v[100:101], v[100:101], v[174:175] op_sel:[0,1] op_sel_hi:[1,1]
	v_pk_add_f32 v[110:111], v[110:111], 1.0 op_sel_hi:[1,0]
	v_rcp_f32_e32 v108, v108
	v_rcp_f32_e32 v109, v109
	v_pk_mul_f32 v[102:103], v[102:103], v[174:175] op_sel:[0,1] op_sel_hi:[1,1]
	v_rcp_f32_e32 v110, v110
	v_rcp_f32_e32 v111, v111
	v_pk_mul_f32 v[100:101], v[100:101], v[108:109]
	s_nop 0
	v_pk_mul_f32 v[102:103], v[102:103], v[110:111]
	v_pk_mul_f32 v[96:97], v[104:105], v[96:97]
	v_pk_mul_f32 v[98:99], v[106:107], v[98:99]
	v_pk_mul_f32 v[104:105], v[104:105], v[174:175] op_sel_hi:[1,0]
	v_pk_mul_f32 v[106:107], v[106:107], v[174:175] op_sel_hi:[1,0]
	v_exp_f32_e32 v104, v104
	v_exp_f32_e32 v105, v105
; #define PG8_GAS __attribute__((address_space(1)))
; __device__ __forceinline__ unsigned pk2_(float lo, float hi) { f32x2c_t v = {lo, hi}; bf16x2c_t b = __builtin_convertvector(v, bf16x2c_t); return __builtin_bit_cast(unsigned, b); }
; __device__ __forceinline__ float silu_f(float x) { return x * __builtin_amdgcn_rcpf(1.0f + __builtin_amdgcn_exp2f(-1.4426950408889634f * x)); }
;     __device__ __forceinline__ void operator()(const f32x4 (&acc)[2][2][4][2], const Unit& u, int wr, int wc, int fr, int fq) const {
;     ...
;             for (int m = 0; m < 4; ++m) {
;                 const int r = row0 + ai * HALF + m * 16; const float s = rs8[ai][m];
;                 float o[8];
; #pragma unroll
;                 for (int n = 0; n < 2; ++n)
; #pragma unroll
;                     for (int i = 0; i < 4; ++i) o[4 * n + i] = silu_f(acc[ai][0][m][n][i] * s) * (acc[ai][1][m][n][i] * s);
;                 u32x4 w; w.x = pk2_(o[0], o[1]); w.y = pk2_(o[2], o[3]); w.z = pk2_(o[4], o[5]); w.w = pk2_(o[6], o[7]);
;                 *(PG8_GAS u32x4*)(O + (size_t)r * 2816 + col0) = w;
	v_exp_f32_e32 v106, v106
	v_exp_f32_e32 v107, v107
	v_pk_add_f32 v[104:105], v[104:105], 1.0 op_sel_hi:[1,0]
	v_pk_mul_f32 v[96:97], v[96:97], v[174:175] op_sel:[0,1] op_sel_hi:[1,1]
	v_pk_add_f32 v[106:107], v[106:107], 1.0 op_sel_hi:[1,0]
	v_rcp_f32_e32 v104, v104
	v_rcp_f32_e32 v105, v105
	v_pk_mul_f32 v[98:99], v[98:99], v[174:175] op_sel:[0,1] op_sel_hi:[1,1]
	v_rcp_f32_e32 v106, v106
	v_rcp_f32_e32 v107, v107
	v_pk_mul_f32 v[96:97], v[96:97], v[104:105]
	s_nop 0
	v_pk_mul_f32 v[98:99], v[98:99], v[106:107]
	v_cvt_pk_bf16_f32 v100, v100, v101
	v_cvt_pk_bf16_f32 v101, v102, v103
	v_cvt_pk_bf16_f32 v102, v96, v97
	v_cvt_pk_bf16_f32 v103, v98, v99
	v_mad_i64_i32 v[104:105], s[6:7], v156, s59, v[170:171]
	v_lshl_add_u64 v[104:105], v[104:105], 0, v[168:169]
	global_store_dwordx4 v[104:105], v[100:103], off
	v_mul_f32_e32 v174, 0xbfb8aa3b, v164
	v_mul_f32_e32 v175, v164, v164
	v_pk_mul_f32 v[84:85], v[92:93], v[84:85]
	v_pk_mul_f32 v[86:87], v[94:95], v[86:87]
	v_pk_mul_f32 v[92:93], v[92:93], v[174:175] op_sel_hi:[1,0]
	v_pk_mul_f32 v[94:95], v[94:95], v[174:175] op_sel_hi:[1,0]
	v_exp_f32_e32 v92, v92
	v_exp_f32_e32 v93, v93
	v_exp_f32_e32 v94, v94
	v_exp_f32_e32 v95, v95
	v_pk_add_f32 v[92:93], v[92:93], 1.0 op_sel_hi:[1,0]
	v_pk_mul_f32 v[84:85], v[84:85], v[174:175] op_sel:[0,1] op_sel_hi:[1,1]
	v_pk_add_f32 v[94:95], v[94:95], 1.0 op_sel_hi:[1,0]
	v_rcp_f32_e32 v92, v92
	v_rcp_f32_e32 v93, v93
	v_pk_mul_f32 v[86:87], v[86:87], v[174:175] op_sel:[0,1] op_sel_hi:[1,1]
	v_rcp_f32_e32 v94, v94
	v_rcp_f32_e32 v95, v95
	v_pk_mul_f32 v[84:85], v[84:85], v[92:93]
	s_nop 0
	v_pk_mul_f32 v[86:87], v[86:87], v[94:95]
	v_pk_mul_f32 v[80:81], v[88:89], v[80:81]
	v_pk_mul_f32 v[82:83], v[90:91], v[82:83]
	v_pk_mul_f32 v[88:89], v[88:89], v[174:175] op_sel_hi:[1,0]
	v_pk_mul_f32 v[90:91], v[90:91], v[174:175] op_sel_hi:[1,0]
	v_exp_f32_e32 v88, v88
	v_exp_f32_e32 v89, v89
	v_exp_f32_e32 v90, v90
	v_exp_f32_e32 v91, v91
	v_pk_add_f32 v[88:89], v[88:89], 1.0 op_sel_hi:[1,0]
	v_pk_mul_f32 v[80:81], v[80:81], v[174:175] op_sel:[0,1] op_sel_hi:[1,1]
	v_pk_add_f32 v[90:91], v[90:91], 1.0 op_sel_hi:[1,0]
	v_rcp_f32_e32 v88, v88
	v_rcp_f32_e32 v89, v89
	v_pk_mul_f32 v[82:83], v[82:83], v[174:175] op_sel:[0,1] op_sel_hi:[1,1]
	v_rcp_f32_e32 v90, v90
	v_rcp_f32_e32 v91, v91
	v_pk_mul_f32 v[80:81], v[80:81], v[88:89]
	s_nop 0
	v_pk_mul_f32 v[82:83], v[82:83], v[90:91]
	v_cvt_pk_bf16_f32 v84, v84, v85
	v_cvt_pk_bf16_f32 v85, v86, v87
	v_cvt_pk_bf16_f32 v86, v80, v81
	v_cvt_pk_bf16_f32 v87, v82, v83
	v_mad_i64_i32 v[88:89], s[6:7], v152, s59, v[170:171]
	v_lshl_add_u64 v[88:89], v[88:89], 0, v[168:169]
	global_store_dwordx4 v[88:89], v[84:87], off
	v_mul_f32_e32 v174, 0xbfb8aa3b, v162
	v_mul_f32_e32 v175, v162, v162
	v_pk_mul_f32 v[68:69], v[76:77], v[68:69]
	v_pk_mul_f32 v[70:71], v[78:79], v[70:71]
	v_pk_mul_f32 v[76:77], v[76:77], v[174:175] op_sel_hi:[1,0]
	v_pk_mul_f32 v[78:79], v[78:79], v[174:175] op_sel_hi:[1,0]
	v_exp_f32_e32 v76, v76
	v_exp_f32_e32 v77, v77
	v_exp_f32_e32 v78, v78
	v_exp_f32_e32 v79, v79
	v_pk_add_f32 v[76:77], v[76:77], 1.0 op_sel_hi:[1,0]
	v_pk_mul_f32 v[68:69], v[68:69], v[174:175] op_sel:[0,1] op_sel_hi:[1,1]
	v_pk_add_f32 v[78:79], v[78:79], 1.0 op_sel_hi:[1,0]
	v_rcp_f32_e32 v76, v76
	v_rcp_f32_e32 v77, v77
	v_pk_mul_f32 v[70:71], v[70:71], v[174:175] op_sel:[0,1] op_sel_hi:[1,1]
	v_rcp_f32_e32 v78, v78
	v_rcp_f32_e32 v79, v79
	v_pk_mul_f32 v[68:69], v[68:69], v[76:77]
	s_nop 0
	v_pk_mul_f32 v[70:71], v[70:71], v[78:79]
	v_pk_mul_f32 v[64:65], v[72:73], v[64:65]
	v_pk_mul_f32 v[66:67], v[74:75], v[66:67]
	v_pk_mul_f32 v[72:73], v[72:73], v[174:175] op_sel_hi:[1,0]
	v_pk_mul_f32 v[74:75], v[74:75], v[174:175] op_sel_hi:[1,0]
	v_exp_f32_e32 v72, v72
	v_exp_f32_e32 v73, v73
	v_exp_f32_e32 v74, v74
	v_exp_f32_e32 v75, v75
	v_pk_add_f32 v[72:73], v[72:73], 1.0 op_sel_hi:[1,0]
	v_pk_mul_f32 v[64:65], v[64:65], v[174:175] op_sel:[0,1] op_sel_hi:[1,1]
	v_pk_add_f32 v[74:75], v[74:75], 1.0 op_sel_hi:[1,0]
	v_rcp_f32_e32 v72, v72
	v_rcp_f32_e32 v73, v73
	v_pk_mul_f32 v[66:67], v[66:67], v[174:175] op_sel:[0,1] op_sel_hi:[1,1]
	v_rcp_f32_e32 v74, v74
	v_rcp_f32_e32 v75, v75
	v_pk_mul_f32 v[64:65], v[64:65], v[72:73]
	s_nop 0
	v_pk_mul_f32 v[66:67], v[66:67], v[74:75]
	v_cvt_pk_bf16_f32 v68, v68, v69
	v_cvt_pk_bf16_f32 v69, v70, v71
	v_cvt_pk_bf16_f32 v70, v64, v65
	v_cvt_pk_bf16_f32 v71, v66, v67
	v_mad_i64_i32 v[72:73], s[6:7], v148, s59, v[170:171]
	v_lshl_add_u64 v[72:73], v[72:73], 0, v[168:169]
	global_store_dwordx4 v[72:73], v[68:71], off
	v_mul_f32_e32 v174, 0xbfb8aa3b, v158
	v_mul_f32_e32 v175, v158, v158
	v_pk_mul_f32 v[52:53], v[60:61], v[52:53]
	v_pk_mul_f32 v[54:55], v[62:63], v[54:55]
	v_pk_mul_f32 v[60:61], v[60:61], v[174:175] op_sel_hi:[1,0]
	v_pk_mul_f32 v[62:63], v[62:63], v[174:175] op_sel_hi:[1,0]
	v_exp_f32_e32 v60, v60
	v_exp_f32_e32 v61, v61
	v_exp_f32_e32 v62, v62
	v_exp_f32_e32 v63, v63
	v_pk_add_f32 v[60:61], v[60:61], 1.0 op_sel_hi:[1,0]
	v_pk_mul_f32 v[52:53], v[52:53], v[174:175] op_sel:[0,1] op_sel_hi:[1,1]
	v_pk_add_f32 v[62:63], v[62:63], 1.0 op_sel_hi:[1,0]
	v_rcp_f32_e32 v60, v60
	v_rcp_f32_e32 v61, v61
	v_pk_mul_f32 v[54:55], v[54:55], v[174:175] op_sel:[0,1] op_sel_hi:[1,1]
	v_rcp_f32_e32 v62, v62
	v_rcp_f32_e32 v63, v63
	v_pk_mul_f32 v[52:53], v[52:53], v[60:61]
	s_nop 0
	v_pk_mul_f32 v[54:55], v[54:55], v[62:63]
	v_pk_mul_f32 v[48:49], v[56:57], v[48:49]
	v_pk_mul_f32 v[50:51], v[58:59], v[50:51]
	v_pk_mul_f32 v[56:57], v[56:57], v[174:175] op_sel_hi:[1,0]
	v_pk_mul_f32 v[58:59], v[58:59], v[174:175] op_sel_hi:[1,0]
	v_exp_f32_e32 v56, v56
	v_exp_f32_e32 v57, v57
	v_exp_f32_e32 v58, v58
; #define PG8_GAS __attribute__((address_space(1)))
; __device__ __forceinline__ unsigned pk2_(float lo, float hi) { f32x2c_t v = {lo, hi}; bf16x2c_t b = __builtin_convertvector(v, bf16x2c_t); return __builtin_bit_cast(unsigned, b); }
; __device__ __forceinline__ float silu_f(float x) { return x * __builtin_amdgcn_rcpf(1.0f + __builtin_amdgcn_exp2f(-1.4426950408889634f * x)); }
;     __device__ __forceinline__ void operator()(const f32x4 (&acc)[2][2][4][2], const Unit& u, int wr, int wc, int fr, int fq) const {
;     ...
;             for (int m = 0; m < 4; ++m) {
;                 const int r = row0 + ai * HALF + m * 16; const float s = rs8[ai][m];
;                 float o[8];
; #pragma unroll
;                 for (int n = 0; n < 2; ++n)
; #pragma unroll
;                     for (int i = 0; i < 4; ++i) o[4 * n + i] = silu_f(acc[ai][0][m][n][i] * s) * (acc[ai][1][m][n][i] * s);
;                 u32x4 w; w.x = pk2_(o[0], o[1]); w.y = pk2_(o[2], o[3]); w.z = pk2_(o[4], o[5]); w.w = pk2_(o[6], o[7]);
;                 *(PG8_GAS u32x4*)(O + (size_t)r * 2816 + col0) = w;
	v_exp_f32_e32 v59, v59
	v_pk_add_f32 v[56:57], v[56:57], 1.0 op_sel_hi:[1,0]
	v_pk_mul_f32 v[48:49], v[48:49], v[174:175] op_sel:[0,1] op_sel_hi:[1,1]
	v_pk_add_f32 v[58:59], v[58:59], 1.0 op_sel_hi:[1,0]
	v_rcp_f32_e32 v56, v56
	v_rcp_f32_e32 v57, v57
	v_pk_mul_f32 v[50:51], v[50:51], v[174:175] op_sel:[0,1] op_sel_hi:[1,1]
	v_rcp_f32_e32 v58, v58
	v_rcp_f32_e32 v59, v59
	v_pk_mul_f32 v[48:49], v[48:49], v[56:57]
	s_nop 0
	v_pk_mul_f32 v[50:51], v[50:51], v[58:59]
	v_cvt_pk_bf16_f32 v52, v52, v53
	v_cvt_pk_bf16_f32 v53, v54, v55
	v_cvt_pk_bf16_f32 v54, v48, v49
	v_cvt_pk_bf16_f32 v55, v50, v51
	v_mad_i64_i32 v[56:57], s[6:7], v146, s59, v[170:171]
	v_lshl_add_u64 v[56:57], v[56:57], 0, v[168:169]
	global_store_dwordx4 v[56:57], v[52:55], off
	v_mul_f32_e32 v174, 0xbfb8aa3b, v154
	v_mul_f32_e32 v175, v154, v154
	v_pk_mul_f32 v[36:37], v[44:45], v[36:37]
	v_pk_mul_f32 v[38:39], v[46:47], v[38:39]
	v_pk_mul_f32 v[44:45], v[44:45], v[174:175] op_sel_hi:[1,0]
	v_pk_mul_f32 v[46:47], v[46:47], v[174:175] op_sel_hi:[1,0]
	v_exp_f32_e32 v44, v44
	v_exp_f32_e32 v45, v45
	v_exp_f32_e32 v46, v46
	v_exp_f32_e32 v47, v47
	v_pk_add_f32 v[44:45], v[44:45], 1.0 op_sel_hi:[1,0]
	v_pk_mul_f32 v[36:37], v[36:37], v[174:175] op_sel:[0,1] op_sel_hi:[1,1]
	v_pk_add_f32 v[46:47], v[46:47], 1.0 op_sel_hi:[1,0]
	v_rcp_f32_e32 v44, v44
	v_rcp_f32_e32 v45, v45
	v_pk_mul_f32 v[38:39], v[38:39], v[174:175] op_sel:[0,1] op_sel_hi:[1,1]
	v_rcp_f32_e32 v46, v46
	v_rcp_f32_e32 v47, v47
	v_pk_mul_f32 v[36:37], v[36:37], v[44:45]
	s_nop 0
	v_pk_mul_f32 v[38:39], v[38:39], v[46:47]
	v_pk_mul_f32 v[32:33], v[40:41], v[32:33]
	v_pk_mul_f32 v[34:35], v[42:43], v[34:35]
	v_pk_mul_f32 v[40:41], v[40:41], v[174:175] op_sel_hi:[1,0]
	v_pk_mul_f32 v[42:43], v[42:43], v[174:175] op_sel_hi:[1,0]
	v_exp_f32_e32 v40, v40
	v_exp_f32_e32 v41, v41
	v_exp_f32_e32 v42, v42
	v_exp_f32_e32 v43, v43
	v_pk_add_f32 v[40:41], v[40:41], 1.0 op_sel_hi:[1,0]
	v_pk_mul_f32 v[32:33], v[32:33], v[174:175] op_sel:[0,1] op_sel_hi:[1,1]
	v_pk_add_f32 v[42:43], v[42:43], 1.0 op_sel_hi:[1,0]
	v_rcp_f32_e32 v40, v40
	v_rcp_f32_e32 v41, v41
	v_pk_mul_f32 v[34:35], v[34:35], v[174:175] op_sel:[0,1] op_sel_hi:[1,1]
	v_rcp_f32_e32 v42, v42
	v_rcp_f32_e32 v43, v43
	v_pk_mul_f32 v[32:33], v[32:33], v[40:41]
	s_nop 0
	v_pk_mul_f32 v[34:35], v[34:35], v[42:43]
	v_cvt_pk_bf16_f32 v36, v36, v37
	v_cvt_pk_bf16_f32 v37, v38, v39
	v_cvt_pk_bf16_f32 v38, v32, v33
	v_cvt_pk_bf16_f32 v39, v34, v35
	v_mad_i64_i32 v[40:41], s[6:7], v144, s59, v[170:171]
	v_lshl_add_u64 v[40:41], v[40:41], 0, v[168:169]
	global_store_dwordx4 v[40:41], v[36:39], off
	v_mul_f32_e32 v174, 0xbfb8aa3b, v150
	v_mul_f32_e32 v175, v150, v150
	v_pk_mul_f32 v[20:21], v[28:29], v[20:21]
	v_pk_mul_f32 v[22:23], v[30:31], v[22:23]
	v_pk_mul_f32 v[28:29], v[28:29], v[174:175] op_sel_hi:[1,0]
	v_pk_mul_f32 v[30:31], v[30:31], v[174:175] op_sel_hi:[1,0]
	v_exp_f32_e32 v28, v28
	v_exp_f32_e32 v29, v29
	v_exp_f32_e32 v30, v30
	v_exp_f32_e32 v31, v31
	v_pk_add_f32 v[28:29], v[28:29], 1.0 op_sel_hi:[1,0]
	v_pk_mul_f32 v[20:21], v[20:21], v[174:175] op_sel:[0,1] op_sel_hi:[1,1]
	v_pk_add_f32 v[30:31], v[30:31], 1.0 op_sel_hi:[1,0]
	v_rcp_f32_e32 v28, v28
	v_rcp_f32_e32 v29, v29
	v_pk_mul_f32 v[22:23], v[22:23], v[174:175] op_sel:[0,1] op_sel_hi:[1,1]
	v_rcp_f32_e32 v30, v30
	v_rcp_f32_e32 v31, v31
	v_pk_mul_f32 v[20:21], v[20:21], v[28:29]
	s_nop 0
	v_pk_mul_f32 v[22:23], v[22:23], v[30:31]
	v_pk_mul_f32 v[16:17], v[24:25], v[16:17]
	v_pk_mul_f32 v[18:19], v[26:27], v[18:19]
	v_pk_mul_f32 v[24:25], v[24:25], v[174:175] op_sel_hi:[1,0]
	v_pk_mul_f32 v[26:27], v[26:27], v[174:175] op_sel_hi:[1,0]
	v_exp_f32_e32 v24, v24
	v_exp_f32_e32 v25, v25
	v_exp_f32_e32 v26, v26
	v_exp_f32_e32 v27, v27
	v_pk_add_f32 v[24:25], v[24:25], 1.0 op_sel_hi:[1,0]
	v_pk_mul_f32 v[16:17], v[16:17], v[174:175] op_sel:[0,1] op_sel_hi:[1,1]
	v_pk_add_f32 v[26:27], v[26:27], 1.0 op_sel_hi:[1,0]
	v_rcp_f32_e32 v24, v24
	v_rcp_f32_e32 v25, v25
	v_pk_mul_f32 v[18:19], v[18:19], v[174:175] op_sel:[0,1] op_sel_hi:[1,1]
	v_rcp_f32_e32 v26, v26
	v_rcp_f32_e32 v27, v27
	v_pk_mul_f32 v[16:17], v[16:17], v[24:25]
	s_nop 0
	v_pk_mul_f32 v[18:19], v[18:19], v[26:27]
	v_cvt_pk_bf16_f32 v20, v20, v21
	v_cvt_pk_bf16_f32 v21, v22, v23
	v_cvt_pk_bf16_f32 v22, v16, v17
	v_cvt_pk_bf16_f32 v23, v18, v19
	v_mad_i64_i32 v[24:25], s[6:7], v142, s59, v[170:171]
	v_lshl_add_u64 v[24:25], v[24:25], 0, v[168:169]
	global_store_dwordx4 v[24:25], v[20:23], off
	v_mul_f32_e32 v174, 0xbfb8aa3b, v132
	v_mul_f32_e32 v175, v132, v132
	v_pk_mul_f32 v[4:5], v[12:13], v[4:5]
	v_pk_mul_f32 v[6:7], v[14:15], v[6:7]
	v_pk_mul_f32 v[12:13], v[12:13], v[174:175] op_sel_hi:[1,0]
	v_pk_mul_f32 v[14:15], v[14:15], v[174:175] op_sel_hi:[1,0]
	v_exp_f32_e32 v12, v12
	v_exp_f32_e32 v13, v13
	v_exp_f32_e32 v14, v14
	v_exp_f32_e32 v15, v15
	v_pk_add_f32 v[12:13], v[12:13], 1.0 op_sel_hi:[1,0]
	v_pk_mul_f32 v[4:5], v[4:5], v[174:175] op_sel:[0,1] op_sel_hi:[1,1]
	v_pk_add_f32 v[14:15], v[14:15], 1.0 op_sel_hi:[1,0]
	v_rcp_f32_e32 v12, v12
	v_rcp_f32_e32 v13, v13
	v_pk_mul_f32 v[6:7], v[6:7], v[174:175] op_sel:[0,1] op_sel_hi:[1,1]
	v_rcp_f32_e32 v14, v14
	v_rcp_f32_e32 v15, v15
	v_pk_mul_f32 v[4:5], v[4:5], v[12:13]
	s_nop 0
	v_pk_mul_f32 v[6:7], v[6:7], v[14:15]
	v_pk_mul_f32 v[0:1], v[8:9], v[0:1]
	v_pk_mul_f32 v[2:3], v[10:11], v[2:3]
	v_pk_mul_f32 v[8:9], v[8:9], v[174:175] op_sel_hi:[1,0]
	v_pk_mul_f32 v[10:11], v[10:11], v[174:175] op_sel_hi:[1,0]
	v_exp_f32_e32 v8, v8
	v_exp_f32_e32 v9, v9
	v_exp_f32_e32 v10, v10
	v_exp_f32_e32 v11, v11
	v_pk_add_f32 v[8:9], v[8:9], 1.0 op_sel_hi:[1,0]
	v_pk_mul_f32 v[0:1], v[0:1], v[174:175] op_sel:[0,1] op_sel_hi:[1,1]
	v_pk_add_f32 v[10:11], v[10:11], 1.0 op_sel_hi:[1,0]
	v_rcp_f32_e32 v8, v8
	v_rcp_f32_e32 v9, v9
	v_pk_mul_f32 v[2:3], v[2:3], v[174:175] op_sel:[0,1] op_sel_hi:[1,1]
	v_rcp_f32_e32 v10, v10
	v_rcp_f32_e32 v11, v11
	v_pk_mul_f32 v[0:1], v[0:1], v[8:9]
	s_nop 0
	v_pk_mul_f32 v[2:3], v[2:3], v[10:11]
	v_cvt_pk_bf16_f32 v4, v4, v5
	v_cvt_pk_bf16_f32 v5, v6, v7
	v_cvt_pk_bf16_f32 v6, v0, v1
	v_cvt_pk_bf16_f32 v7, v2, v3
	v_mad_i64_i32 v[8:9], s[6:7], v140, s59, v[170:171]
	v_lshl_add_u64 v[8:9], v[8:9], 0, v[168:169]
	s_andn2_b64 vcc, exec, s[4:5]
	s_mov_b64 s[4:5], -1
	global_store_dwordx4 v[8:9], v[4:7], off
	s_cbranch_vccnz .LBB0_690
	s_andn2_b64 vcc, exec, s[12:13]
	s_cbranch_vccnz .LBB0_689
	s_barrier
	s_branch .LBB0_689

; #define GAS __attribute__((address_space(1)))
; __device__ __forceinline__ void indexer_unit(const Args& a, LAS unsigned char* lds, LAS unsigned long long* maskl, int b, int qblk, int wave, int lane) {
;     ...
;     const int fr = lane & 15, fq = lane >> 4, t0 = qblk * 16; const size_t rowb = (size_t)b * SEQ;
;     bf16x8 af[8][2]; float wv[8][4];
; #pragma unroll
;     for (int rt = 0; rt < 8; ++rt) {
;         const GAS bf16* p = z + (rowb + t0 + 2 * rt + (fr >> 3)) * ZW + ZIQ + (fr & 7) * 64 + 8 * fq;
;         af[rt][0] = __builtin_nontemporal_load((const GAS bf16x8*)p); af[rt][1] = __builtin_nontemporal_load((const GAS bf16x8*)(p + 32));
;         const u32x2 w = *(const GAS u32x2*)(z + (rowb + t0 + 2 * rt + (fq >> 1)) * ZW + ZIW + 4 * (fq & 1));
;         wv[rt][0] = bflo(w.x); wv[rt][1] = bfhi(w.x); wv[rt][2] = bflo(w.y); wv[rt][3] = bfhi(w.y);
;     }
;     const int nkt = qblk + 1;
;     bf16x8 nb0, nb1;
;     { const int k0 = wave < nkt ? wave : 0; const GAS bf16* p = ikn + (rowb + 16 * k0 + fr) * 64 + 8 * fq; nb0 = *(const GAS bf16x8*)p; nb1 = *(const GAS bf16x8*)(p + 32); }
;     for (int kt = wave; kt < nkt; kt += 8) {
;         const int key = 16 * kt + fr;
;         const bf16x8 b0 = nb0, b1 = nb1;
;         { const int k2 = kt + 8 < nkt ? kt + 8 : kt; const GAS bf16* p = ikn + (rowb + 16 * k2 + fr) * 64 + 8 * fq; nb0 = *(const GAS bf16x8*)p; nb1 = *(const GAS bf16x8*)(p + 32); }
.LBB0_1082:
	v_readlane_b32 s2, v254, 44
	v_mov_b32_e32 v76, v252
	s_or_b32 s9, s8, s2
	s_lshl_b32 s76, s9, 4
	v_and_b32_e32 v5, 63, v76
	v_readlane_b32 s2, v254, 4
	s_cmp_gt_u32 s2, s9
	v_lshlrev_b32_e32 v84, 6, v5
	s_cbranch_scc1 .Lhs_skip
	v_readlane_b32 s14, v254, 46
	v_readlane_b32 s4, v254, 24
	s_add_i32 s2, s76, s14
	v_bfe_u32 v57, v76, 3, 1
	v_readlane_b32 s5, v254, 25
	v_and_b32_e32 v2, 0x1c0, v84
	s_nop 0
	v_mov_b64_e32 v[46:47], s[4:5]
	s_movk_i32 s10, 0x1e00
	v_lshlrev_b32_e32 v48, 1, v2
	v_mov_b32_e32 v49, v4
	v_lshrrev_b32_e32 v119, 5, v5
	v_lshlrev_b32_e32 v74, 4, v5
	v_mov_b32_e32 v75, v4
	s_mov_b64 s[12:13], 0x1900
	s_or_b32 s3, s2, 2
	s_movk_i32 s11, 0x1000
	s_or_b32 s3, s2, 4
	s_or_b32 s3, s2, 6
	s_or_b32 s3, s2, 8
	s_or_b32 s3, s2, 10
	s_or_b32 s3, s2, 12
	v_or_b32_e32 v54, s3, v57
	v_mad_u64_u32 v[54:55], s[4:5], v54, s10, v[46:47]
	v_lshl_add_u64 v[54:55], v[54:55], 0, v[48:49]
	v_lshl_add_u64 v[54:55], v[54:55], 0, v[74:75]
	v_add_co_u32_e32 v56, vcc, s11, v54
	s_mov_b64 s[6:7], vcc
	s_or_b32 s4, s2, 14
	v_and_b32_e32 v77, 15, v76
	v_readlane_b32 s2, v254, 47
	s_nop 1
	v_mov_b32_e32 v66, s2
	v_mov_b32_e32 v67, v4
	v_readlane_b32 s2, v254, 26
	v_lshlrev_b64 v[66:67], 7, v[66:67]
	v_readlane_b32 s3, v254, 27
	s_nop 1
	v_lshl_add_u64 v[66:67], s[2:3], 0, v[66:67]
	v_lshl_add_u64 v[70:71], v[66:67], 0, v[74:75]
	v_cmp_lt_i32_e32 vcc, v227, v226
	global_load_dwordx4 v[66:69], v[70:71], off offset:1024
	global_load_dwordx4 v[70:73], v[70:71], off
	v_readlane_b32 s98, v254, 24
	v_readlane_b32 s99, v254, 25
	v_readlane_b32 s100, v254, 46
	v_bfe_u32 v86, v252, 3, 1
	v_lshrrev_b32_e32 v87, 5, v5
	v_and_b32_e32 v88, 7, v5
	s_add_i32 s100, s100, s76
	s_add_i32 s100, s100, s85
	v_and_b32_e32 v89, 48, v5
	v_lshl_or_b32 v88, v88, 7, v89
	v_or_b32_e32 v86, s100, v86
	v_or_b32_e32 v87, s100, v87
	s_movk_i32 s101, 0x1900
	s_movk_i32 s100, 0x1d90
	v_mul_u32_u24_e32 v86, 0x1e00, v86
	v_mul_u32_u24_e32 v87, 0x1e00, v87
	v_lshrrev_b32_e32 v89, 1, v5
	v_and_b32_e32 v89, 8, v89
	v_add3_u32 v86, v86, v88, s101
	v_add3_u32 v87, v87, v89, s100
	s_lshl_b32 s100, s85, 10
	s_mov_b32 m0, s100
	s_lshl_b32 s101, s85, 8
	global_load_lds_dwordx4 v86, s[98:99] nt
	s_add_i32 s100, s100, 0x3c0
	s_mov_b32 m0, s100
	v_lshl_add_u32 v89, v5, 3, s101
	global_load_lds_dwordx4 v86, s[98:99] offset:64 nt
	global_load_dwordx2 v[98:99], v87, s[98:99]
	s_waitcnt vmcnt(0)
	ds_write_b64 v89, v[98:99] offset:16384
	s_waitcnt lgkmcnt(0)
	s_barrier
	v_lshlrev_b32_e32 v88, 4, v5
	v_lshlrev_b32_e32 v89, 3, v5
	ds_read_b128 v[0:3], v88 offset:0
	ds_read_b128 v[6:9], v88 offset:1024
	ds_read_b128 v[14:17], v88 offset:2048
	ds_read_b128 v[10:13], v88 offset:3072
	ds_read_b128 v[18:21], v88 offset:4096
	ds_read_b128 v[22:25], v88 offset:5120
	ds_read_b128 v[30:33], v88 offset:6144
	ds_read_b128 v[26:29], v88 offset:7168
	ds_read_b128 v[34:37], v88 offset:8192
	ds_read_b128 v[38:41], v88 offset:9216
	ds_read_b128 v[42:45], v88 offset:10240
	ds_read_b128 v[50:53], v88 offset:11264
	ds_read_b128 v[54:57], v88 offset:12288
	ds_read_b128 v[58:61], v88 offset:13312
	ds_read_b128 v[46:49], v88 offset:14336
	ds_read_b128 v[62:65], v88 offset:15360
	ds_read_b64 v[78:79], v89 offset:16384
	ds_read_b64 v[80:81], v89 offset:16896
	ds_read_b64 v[82:83], v89 offset:17408
	ds_read_b64 v[100:101], v89 offset:17920
	ds_read_b64 v[104:105], v89 offset:18432
	ds_read_b64 v[108:109], v89 offset:18944
	ds_read_b64 v[112:113], v89 offset:19456
	ds_read_b64 v[116:117], v89 offset:19968
	s_waitcnt lgkmcnt(0)
	s_barrier
	s_waitcnt vmcnt(0)
	v_lshlrev_b32_e32 v93, 16, v82
	v_and_b32_e32 v94, 0xffff0000, v82
	v_lshlrev_b32_e32 v95, 16, v83
	v_and_b32_e32 v96, 0xffff0000, v83
	v_lshl_add_u64 v[82:83], s[2:3], 0, v[74:75]
	v_cndmask_b32_e32 v74, v253, v227, vcc
	v_lshlrev_b32_e32 v118, 2, v74
	v_and_b32_e32 v74, 16, v76
	v_cmp_eq_u32_e64 s[6:7], 0, v74
	v_lshlrev_b32_e32 v74, 2, v77
	v_lshl_or_b32 v74, v119, 13, v74
	v_readlane_b32 s2, v254, 36
	v_lshlrev_b32_e32 v85, 16, v78
	v_and_b32_e32 v86, 0xffff0000, v78
	v_lshlrev_b32_e32 v87, 16, v79
	v_and_b32_e32 v88, 0xffff0000, v79
	v_lshlrev_b32_e32 v89, 16, v80
	v_and_b32_e32 v90, 0xffff0000, v80
	v_lshlrev_b32_e32 v91, 16, v81
	v_and_b32_e32 v92, 0xffff0000, v81
	v_lshlrev_b32_e32 v97, 16, v100
	v_and_b32_e32 v98, 0xffff0000, v100
	v_lshlrev_b32_e32 v99, 16, v101
	v_and_b32_e32 v100, 0xffff0000, v101
	v_lshlrev_b32_e32 v101, 16, v104
	v_and_b32_e32 v102, 0xffff0000, v104
	v_lshlrev_b32_e32 v103, 16, v105
	v_and_b32_e32 v104, 0xffff0000, v105
	v_lshlrev_b32_e32 v105, 16, v108
	v_and_b32_e32 v106, 0xffff0000, v108
	v_lshlrev_b32_e32 v107, 16, v109
	v_and_b32_e32 v108, 0xffff0000, v109
	v_add_u32_e32 v119, s2, v74
	v_readlane_b32 s10, v254, 4
	v_lshlrev_b32_e32 v109, 16, v112
	v_and_b32_e32 v110, 0xffff0000, v112
	v_lshlrev_b32_e32 v111, 16, v113
	v_and_b32_e32 v112, 0xffff0000, v113
	v_lshlrev_b32_e32 v113, 16, v116
	v_and_b32_e32 v114, 0xffff0000, v116
	v_lshlrev_b32_e32 v115, 16, v117
	v_and_b32_e32 v116, 0xffff0000, v117
	v_mov_b32_e32 v117, s14
	s_branch .LBB0_1085

; __device__ __forceinline__ void xattn_unit(const Args& a, LAS unsigned char* lds, int b, int h, int qb, int tid, int wave, int lane) {
;     ...
;     const int fr = lane & 15, fq = lane >> 4; const size_t qrow = (size_t)b * SEQ + qb * 128 + 16 * wave + fr;
;     bf16x8 qf[8];
; #pragma unroll
;     for (int kk = 0; kk < 8; ++kk) qf[kk] = *(const GAS bf16x8*)(QX + qrow * DM + h * 256 + 32 * kk + 8 * fq);
;     u32x4 rr[2][4];
;     const unsigned vok = (unsigned)((tid >> 5) * DM + 8 * (tid & 31)) * 2u, vov = (unsigned)((tid >> 3) * MEMR + 8 * (tid & 7)) * 2u;
;     const GAS char* kxb = (const GAS char*)KX + ((size_t)b * 256 * DM + h * 256) * 2; const GAS char* vxb = (const GAS char*)VTX + ((size_t)h * 256 * MEMR + b * 256) * 2;
;     auto gload = [&](int j) {
;         if (j < 4) { const GAS char* p_ = kxb + (size_t)j * (64 * DM * 2);
; #pragma unroll
;             for (int i = 0; i < 4; ++i) rr[j & 1][i] = *(const GAS u32x4*)(p_ + (size_t)(vok + (unsigned)(i * 16 * DM * 2)));
;         } else { const GAS char* p_ = vxb + (size_t)(j - 4) * 128;
; #pragma unroll
;             for (int i = 0; i < 4; ++i) rr[j & 1][i] = *(const GAS u32x4*)(p_ + (size_t)(vov + (unsigned)(i * 64 * MEMR * 2)));
;         }
;     };
;     auto lstore = [&](int j) {
;         LAS bf16* base = (LAS bf16*)(lds + (j & 1) * STG);
;         if (j < 4) {
; #pragma unroll
;             for (int i = 0; i < 4; ++i) { const int id = tid + 512 * i; *(LAS u32x4*)(base + (id >> 5) * KS + 8 * (id & 31)) = rr[j & 1][i]; }
;         } else {
; #pragma unroll
;             for (int i = 0; i < 4; ++i) { const int id = tid + 512 * i; *(LAS u32x4*)(base + (id >> 3) * VS + 8 * (id & 7)) = rr[j & 1][i]; }
;         }
;     };
;     f32x4 S[16]; bf16x8 pf[8]; f32x4 O[16]; float l = 0.f;
; #pragma unroll
;     for (int i = 0; i < 16; ++i) { S[i] = (f32x4){0.f, 0.f, 0.f, 0.f}; O[i] = (f32x4){0.f, 0.f, 0.f, 0.f}; }
;     gload(0); gload(1); lstore(0); __syncthreads();
; #pragma unroll
;     for (int j = 0; j < 8; ++j) {
;         if (j < 6) gload(j + 2);
;         const LAS bf16* base = (const LAS bf16*)(lds + (j & 1) * STG);
;         if (j < 4) {
; #pragma unroll
;             for (int rt = 0; rt < 4; ++rt)
; #pragma unroll
;                 for (int kk = 0; kk < 8; ++kk) S[4 * j + rt] = mfma16(*(const LAS bf16x8*)(base + (16 * rt + fr) * KS + 32 * kk + 8 * fq), qf[kk], S[4 * j + rt]);
.LBB0_1518:
	s_ashr_i32 s0, s10, 4
	s_and_b32 s6, s17, 0x780
	s_add_i32 s7, s0, s12
	v_mov_b32_e32 v200, v252
	s_and_b32 s23, s0, 3
	s_add_i32 s0, s6, s70
	s_ashr_i32 s6, s7, 2
	s_ashr_i32 s7, s6, 31
	v_lshlrev_b32_e32 v192, 4, v200
	v_add_u32_e32 v216, 0x200, v200
	v_lshlrev_b32_e32 v2, 6, v200
	v_and_b32_e32 v4, 0x1f0, v192
	v_ashrrev_i32_e32 v5, 5, v216
	s_lshl_b64 s[8:9], s[6:7], 11
	v_and_b32_e32 v213, 15, v200
	v_and_or_b32 v193, v2, s18, v4
	v_mul_lo_u32 v2, v5, s20
	s_add_u32 s0, s8, s0
	v_add3_u32 v212, 0, v2, v4
	s_addc_u32 s24, s9, 0
	v_or_b32_e32 v2, s0, v213
	s_lshl_b32 s0, s23, 9
	s_lshl_b64 s[8:9], s[6:7], 19
	v_ashrrev_i32_e32 v3, 5, v200
	v_add_u32_e32 v217, 0x400, v200
	s_add_u32 s8, s13, s8
	v_mul_lo_u32 v3, v3, s20
	v_ashrrev_i32_e32 v6, 5, v217
	s_addc_u32 s9, s14, s9
	s_lshl_b32 s6, s6, 8
	v_add3_u32 v211, 0, v3, v4
	v_mul_lo_u32 v3, v6, s20
	s_lshl_b32 s7, s23, 20
	s_ashr_i32 s23, s6, 31
	v_add3_u32 v224, 0, v3, v4
	v_mov_b32_e32 v3, s24
	s_add_u32 s6, s6, s7
	v_lshlrev_b64 v[202:203], 11, v[2:3]
	s_addc_u32 s7, s23, 0
	v_add_u32_e32 v218, 0x600, v200
	v_lshl_add_u64 v[2:3], s[2:3], 0, v[202:203]
	s_lshl_b64 s[6:7], s[6:7], 1
	v_mov_b32_e32 v1, v201
	v_and_b32_e32 v214, 63, v200
	v_and_b32_e32 v0, 48, v200
	v_ashrrev_i32_e32 v7, 5, v218
	v_lshl_add_u64 v[2:3], v[2:3], 0, s[0:1]
	s_add_u32 s8, s8, s0
	v_add_u32_e32 v8, 0, v0
	v_or_b32_e32 v215, 48, v214
	v_mul_lo_u32 v5, v7, s20
	v_lshl_add_u64 v[12:13], v[2:3], 0, v[0:1]
	s_addc_u32 s9, s9, 0
	v_mad_u32_u24 v210, v213, s20, v8
	v_mad_u32_u24 v209, v215, s20, v8
	v_add_u32_e32 v194, 0x8000, v193
	v_add_u32_e32 v195, 0x10000, v193
	v_add_u32_e32 v196, 0x18000, v193
	v_add3_u32 v225, 0, v5, v4
	global_load_dwordx4 v[156:159], v[12:13], off
	global_load_dwordx4 v[120:123], v[12:13], off offset:64
	global_load_dwordx4 v[112:115], v[12:13], off offset:128
	global_load_dwordx4 v[104:107], v[12:13], off offset:192
	global_load_dwordx4 v[28:31], v[12:13], off offset:256
	global_load_dwordx4 v[8:11], v[12:13], off offset:320
	global_load_dwordx4 v[4:7], v[12:13], off offset:384
	global_load_dwordx4 v[0:3], v[12:13], off offset:448
	s_nop 0
	global_load_dwordx4 v[12:15], v193, s[8:9]
	global_load_dwordx4 v[16:19], v194, s[8:9]
	global_load_dwordx4 v[20:23], v195, s[8:9]
	global_load_dwordx4 v[24:27], v196, s[8:9]
	s_add_u32 s6, s15, s6
	s_addc_u32 s7, s16, s7
	s_add_u32 s24, s8, 0x20000
	s_addc_u32 s25, s9, 0
	global_load_dwordx4 v[32:35], v193, s[24:25]
	global_load_dwordx4 v[36:39], v194, s[24:25]
	global_load_dwordx4 v[40:43], v195, s[24:25]
	global_load_dwordx4 v[44:47], v196, s[24:25]
	s_add_u32 s24, s8, 0x40000
	s_addc_u32 s25, s9, 0
	s_add_u32 s8, s8, 0x60000
	s_addc_u32 s9, s9, 0
	v_and_b32_e32 v219, 0x70, v192
	v_lshrrev_b32_e32 v216, 3, v216
	v_cmp_lt_i32_e32 vcc, v227, v226
	s_add_i32 s10, s10, 1
	s_addk_i32 s17, 0x80
	s_cmp_ge_i32 s10, s11
	s_waitcnt vmcnt(0)
	ds_write_b128 v211, v[12:15]
	ds_write_b128 v212, v[16:19]
	ds_write_b128 v224, v[20:23]
	ds_write_b128 v225, v[24:27]
	s_waitcnt lgkmcnt(0)
	s_barrier
	global_load_dwordx4 v[12:15], v193, s[24:25]
	global_load_dwordx4 v[16:19], v194, s[24:25]
	global_load_dwordx4 v[20:23], v195, s[24:25]
	global_load_dwordx4 v[24:27], v196, s[24:25]
	ds_read_b128 v[48:51], v210
	ds_read_b128 v[52:55], v210 offset:64
	ds_read_b128 v[56:59], v210 offset:128
	ds_read_b128 v[60:63], v210 offset:192
	ds_read_b128 v[64:67], v210 offset:256
	ds_read_b128 v[68:71], v210 offset:320
	ds_read_b128 v[72:75], v210 offset:384
	ds_read_b128 v[76:79], v210 offset:448
	ds_read_b128 v[80:83], v210 offset:8448
	ds_read_b128 v[84:87], v210 offset:8512
	ds_read_b128 v[88:91], v210 offset:8576
	ds_read_b128 v[92:95], v210 offset:8640
	ds_read_b128 v[96:99], v210 offset:8704
	ds_read_b128 v[100:103], v210 offset:8768
	ds_read_b128 v[108:111], v210 offset:8832
	ds_read_b128 v[116:119], v210 offset:8896
	ds_read_b128 v[124:127], v210 offset:16896
	ds_read_b128 v[128:131], v210 offset:16960
	s_waitcnt lgkmcnt(14)
	v_mfma_f32_16x16x32_bf16 v[48:51], v[48:51], v[156:159], 0
	ds_read_b128 v[132:135], v210 offset:17024
	ds_read_b128 v[136:139], v210 offset:17088
	ds_read_b128 v[140:143], v209
	ds_read_b128 v[144:147], v210 offset:17152
	ds_read_b128 v[148:151], v210 offset:17216
	ds_read_b128 v[152:155], v210 offset:17280
	ds_read_b128 v[160:163], v210 offset:17344
	ds_read_b128 v[164:167], v209 offset:64
	ds_read_b128 v[168:171], v209 offset:128
	s_waitcnt lgkmcnt(14)
	v_mfma_f32_16x16x32_bf16 v[80:83], v[80:83], v[156:159], 0
	ds_read_b128 v[172:175], v209 offset:192
	ds_read_b128 v[176:179], v209 offset:256
	ds_read_b128 v[180:183], v209 offset:320
	s_waitcnt lgkmcnt(13)
	v_mfma_f32_16x16x32_bf16 v[124:127], v[124:127], v[156:159], 0
	v_mfma_f32_16x16x32_bf16 v[48:51], v[52:55], v[120:123], v[48:51]
	ds_read_b128 v[52:55], v209 offset:384
	ds_read_b128 v[184:187], v209 offset:448
	ds_write_b128 v211, v[32:35] offset:36864
	ds_write_b128 v212, v[36:39] offset:36864
	ds_write_b128 v224, v[40:43] offset:36864
	ds_write_b128 v225, v[44:47] offset:36864
	v_mfma_f32_16x16x32_bf16 v[32:35], v[84:87], v[120:123], v[80:83]
	s_waitcnt lgkmcnt(0)
	s_barrier
; #define LAS __attribute__((address_space(3)))
; __device__ __forceinline__ f32x4 mfma16(bf16x8 a, bf16x8 b, f32x4 c) { return __builtin_amdgcn_mfma_f32_16x16x32_bf16(a, b, c, 0, 0, 0); }
; __device__ __forceinline__ bf16x8 pack8(f32x4 a, f32x4 b) { u32x4 w; w.x = pk2(a[0], a[1]); w.y = pk2(a[2], a[3]); w.z = pk2(b[0], b[1]); w.w = pk2(b[2], b[3]); return __builtin_bit_cast(bf16x8, w); }
; __device__ __forceinline__ void xattn_unit(const Args& a, LAS unsigned char* lds, int b, int h, int qb, int tid, int wave, int lane) {
;     ...
;     gload(0); gload(1); lstore(0); __syncthreads();
; #pragma unroll
;     for (int j = 0; j < 8; ++j) {
;         if (j < 6) gload(j + 2);
;         const LAS bf16* base = (const LAS bf16*)(lds + (j & 1) * STG);
;         if (j < 4) {
; #pragma unroll
;             for (int rt = 0; rt < 4; ++rt)
; #pragma unroll
;                 for (int kk = 0; kk < 8; ++kk) S[4 * j + rt] = mfma16(*(const LAS bf16x8*)(base + (16 * rt + fr) * KS + 32 * kk + 8 * fq), qf[kk], S[4 * j + rt]);
;             if (j == 3) {
;                 float mx = -3.0e38f;
; #pragma unroll
;                 for (int i = 0; i < 16; ++i) mx = fmaxf(mx, fmaxf(fmaxf(S[i][0], S[i][1]), fmaxf(S[i][2], S[i][3])));
;                 mx = fmaxf(mx, __shfl_xor(mx, 16)); mx = fmaxf(mx, __shfl_xor(mx, 32));
; #pragma unroll
;                 for (int i = 0; i < 16; ++i)
; #pragma unroll
;                     for (int k = 0; k < 4; ++k) { S[i][k] = __builtin_amdgcn_exp2f(S[i][k] - mx); l += S[i][k]; }
;                 l += __shfl_xor(l, 16); l += __shfl_xor(l, 32);
; #pragma unroll
;                 for (int c2 = 0; c2 < 8; ++c2) pf[c2] = pack8(S[2 * c2], S[2 * c2 + 1]);
;             }
;         } else {
;             const int mt = j - 4;
; #pragma unroll
;             for (int dt = 0; dt < 16; ++dt) {
;                 const LAS bf16* vr = base + (16 * dt + fr) * VS + 4 * fq;
;                 O[dt] = mfma16(cat8(*(const LAS u32x2*)vr, *(const LAS u32x2*)(vr + 16)), pf[2 * mt], O[dt]);
;                 O[dt] = mfma16(cat8(*(const LAS u32x2*)(vr + 32), *(const LAS u32x2*)(vr + 48)), pf[2 * mt + 1], O[dt]);
;             }
;         }
;         if (j < 7) lstore(j + 1);
;         __syncthreads();
	ds_read_b128 v[44:47], v210 offset:36864
	ds_read_b128 v[80:83], v210 offset:36928
	v_mfma_f32_16x16x32_bf16 v[140:143], v[140:143], v[156:159], 0
	v_mfma_f32_16x16x32_bf16 v[36:39], v[128:131], v[120:123], v[124:127]
	ds_read_b128 v[84:87], v210 offset:45312
	s_nop 1
	ds_read_b128 v[124:127], v210 offset:45376
	s_waitcnt lgkmcnt(3)
	v_mfma_f32_16x16x32_bf16 v[44:47], v[44:47], v[156:159], 0
	v_mfma_f32_16x16x32_bf16 v[48:51], v[56:59], v[112:115], v[48:51]
	v_mfma_f32_16x16x32_bf16 v[40:43], v[164:167], v[120:123], v[140:143]
	ds_read_b128 v[128:131], v210 offset:53760
	s_nop 1
	ds_read_b128 v[140:143], v210 offset:53824
	ds_read_b128 v[164:167], v209 offset:36864
	ds_read_b128 v[188:191], v209 offset:36928
	s_waitcnt lgkmcnt(5)
	v_mfma_f32_16x16x32_bf16 v[84:87], v[84:87], v[156:159], 0
	v_mfma_f32_16x16x32_bf16 v[32:35], v[88:91], v[112:115], v[32:35]
	v_mfma_f32_16x16x32_bf16 v[44:47], v[80:83], v[120:123], v[44:47]
	v_mfma_f32_16x16x32_bf16 v[48:51], v[60:63], v[104:107], v[48:51]
	ds_read_b128 v[60:63], v210 offset:36992
	ds_read_b128 v[88:91], v210 offset:37056
	s_waitcnt lgkmcnt(5)
	v_mfma_f32_16x16x32_bf16 v[128:131], v[128:131], v[156:159], 0
	v_mfma_f32_16x16x32_bf16 v[56:59], v[124:127], v[120:123], v[84:87]
	v_mfma_f32_16x16x32_bf16 v[32:35], v[92:95], v[104:107], v[32:35]
	s_waitcnt lgkmcnt(1)
	v_mfma_f32_16x16x32_bf16 v[44:47], v[60:63], v[112:115], v[44:47]
	ds_read_b128 v[60:63], v210 offset:45440
	ds_read_b128 v[92:95], v210 offset:45504
	v_mfma_f32_16x16x32_bf16 v[164:167], v[164:167], v[156:159], 0
	v_mfma_f32_16x16x32_bf16 v[80:83], v[140:143], v[120:123], v[128:131]
	s_waitcnt lgkmcnt(1)
	v_mfma_f32_16x16x32_bf16 v[56:59], v[60:63], v[112:115], v[56:59]
	ds_read_b128 v[60:63], v210 offset:53888
	ds_read_b128 v[124:127], v210 offset:53952
	v_mfma_f32_16x16x32_bf16 v[84:87], v[188:191], v[120:123], v[164:167]
	s_waitcnt lgkmcnt(1)
	v_mfma_f32_16x16x32_bf16 v[60:63], v[60:63], v[112:115], v[80:83]
	s_nop 2
	ds_read_b128 v[80:83], v209 offset:36992
	ds_read_b128 v[128:131], v209 offset:37056
	v_mfma_f32_16x16x32_bf16 v[40:43], v[168:171], v[112:115], v[40:43]
	s_waitcnt lgkmcnt(1)
	v_mfma_f32_16x16x32_bf16 v[80:83], v[80:83], v[112:115], v[84:87]
	v_mfma_f32_16x16x32_bf16 v[48:51], v[64:67], v[28:31], v[48:51]
	v_mfma_f32_16x16x32_bf16 v[40:43], v[172:175], v[104:107], v[40:43]
	v_mfma_f32_16x16x32_bf16 v[44:47], v[88:91], v[104:107], v[44:47]
	s_waitcnt lgkmcnt(0)
	v_mfma_f32_16x16x32_bf16 v[64:67], v[128:131], v[104:107], v[80:83]
	v_mfma_f32_16x16x32_bf16 v[48:51], v[68:71], v[8:11], v[48:51]
	ds_read_b128 v[68:71], v210 offset:37120
	s_nop 0
	ds_read_b128 v[80:83], v210 offset:37184
	v_mfma_f32_16x16x32_bf16 v[32:35], v[96:99], v[28:31], v[32:35]
	v_mfma_f32_16x16x32_bf16 v[40:43], v[176:179], v[28:31], v[40:43]
	v_mfma_f32_16x16x32_bf16 v[56:59], v[92:95], v[104:107], v[56:59]
	s_waitcnt lgkmcnt(1)
	v_mfma_f32_16x16x32_bf16 v[44:47], v[68:71], v[28:31], v[44:47]
	ds_read_b128 v[68:71], v210 offset:45568
	ds_read_b128 v[84:87], v210 offset:45632
	v_mfma_f32_16x16x32_bf16 v[36:39], v[132:135], v[112:115], v[36:39]
	v_mfma_f32_16x16x32_bf16 v[60:63], v[124:127], v[104:107], v[60:63]
	v_mfma_f32_16x16x32_bf16 v[32:35], v[100:103], v[8:11], v[32:35]
	v_mfma_f32_16x16x32_bf16 v[40:43], v[180:183], v[8:11], v[40:43]
	s_waitcnt lgkmcnt(1)
	v_mfma_f32_16x16x32_bf16 v[56:59], v[68:71], v[28:31], v[56:59]
	ds_read_b128 v[68:71], v210 offset:54016
	ds_read_b128 v[88:91], v210 offset:54080
	v_mfma_f32_16x16x32_bf16 v[36:39], v[136:139], v[104:107], v[36:39]
	s_waitcnt lgkmcnt(1)
	v_mfma_f32_16x16x32_bf16 v[60:63], v[68:71], v[28:31], v[60:63]
	ds_read_b128 v[68:71], v209 offset:37120
	ds_read_b128 v[92:95], v209 offset:37184
	v_mfma_f32_16x16x32_bf16 v[48:51], v[72:75], v[4:7], v[48:51]
	v_mfma_f32_16x16x32_bf16 v[32:35], v[108:111], v[4:7], v[32:35]
	v_mfma_f32_16x16x32_bf16 v[52:55], v[52:55], v[4:7], v[40:43]
	v_mfma_f32_16x16x32_bf16 v[36:39], v[144:147], v[28:31], v[36:39]
	s_waitcnt lgkmcnt(1)
	v_mfma_f32_16x16x32_bf16 v[64:67], v[68:71], v[28:31], v[64:67]
	v_mfma_f32_16x16x32_bf16 v[68:71], v[80:83], v[8:11], v[44:47]
	v_mfma_f32_16x16x32_bf16 v[44:47], v[76:79], v[0:3], v[48:51]
	v_mfma_f32_16x16x32_bf16 v[40:43], v[116:119], v[0:3], v[32:35]
	v_mfma_f32_16x16x32_bf16 v[32:35], v[184:187], v[0:3], v[52:55]
	s_nop 0
	ds_read_b128 v[48:51], v210 offset:37248
	s_nop 0
	ds_read_b128 v[52:55], v210 offset:37312
	v_mfma_f32_16x16x32_bf16 v[36:39], v[148:151], v[8:11], v[36:39]
	v_mfma_f32_16x16x32_bf16 v[56:59], v[84:87], v[8:11], v[56:59]
	v_lshlrev_b32_e32 v84, 10, v200
	v_and_or_b32 v205, v84, s19, v219
	v_add_u32_e32 v206, 0x80000, v205
	s_waitcnt lgkmcnt(1)
	v_mfma_f32_16x16x32_bf16 v[48:51], v[48:51], v[4:7], v[68:71]
	s_nop 2
	ds_read_b128 v[68:71], v210 offset:45696
	ds_read_b128 v[72:75], v210 offset:45760
	v_add_u32_e32 v207, 0x100000, v205
	v_add_u32_e32 v208, 0x180000, v205
	v_mfma_f32_16x16x32_bf16 v[36:39], v[152:155], v[4:7], v[36:39]
	v_mfma_f32_16x16x32_bf16 v[60:63], v[88:91], v[8:11], v[60:63]
	s_waitcnt lgkmcnt(1)
	v_mfma_f32_16x16x32_bf16 v[56:59], v[68:71], v[4:7], v[56:59]
	ds_read_b128 v[68:71], v210 offset:54144
	ds_read_b128 v[76:79], v210 offset:54208
	v_mfma_f32_16x16x32_bf16 v[36:39], v[160:163], v[0:3], v[36:39]
	s_waitcnt lgkmcnt(1)
	v_mfma_f32_16x16x32_bf16 v[60:63], v[68:71], v[4:7], v[60:63]
	ds_read_b128 v[68:71], v209 offset:37248
	ds_read_b128 v[80:83], v209 offset:37312
	global_load_dwordx4 v[160:163], v193, s[8:9]
	global_load_dwordx4 v[164:167], v194, s[8:9]
	global_load_dwordx4 v[168:171], v195, s[8:9]
	global_load_dwordx4 v[172:175], v196, s[8:9]
	v_mfma_f32_16x16x32_bf16 v[64:67], v[92:95], v[8:11], v[64:67]
	s_waitcnt vmcnt(7)
	ds_write_b128 v211, v[12:15]
	s_waitcnt vmcnt(6)
	ds_write_b128 v212, v[16:19]
	s_waitcnt vmcnt(5)
	ds_write_b128 v224, v[20:23]
	s_waitcnt vmcnt(4)
	ds_write_b128 v225, v[24:27]
	s_waitcnt lgkmcnt(0)
	s_barrier
; #define LAS __attribute__((address_space(3)))
; __device__ __forceinline__ f32x4 mfma16(bf16x8 a, bf16x8 b, f32x4 c) { return __builtin_amdgcn_mfma_f32_16x16x32_bf16(a, b, c, 0, 0, 0); }
; __device__ __forceinline__ bf16x8 pack8(f32x4 a, f32x4 b) { u32x4 w; w.x = pk2(a[0], a[1]); w.y = pk2(a[2], a[3]); w.z = pk2(b[0], b[1]); w.w = pk2(b[2], b[3]); return __builtin_bit_cast(bf16x8, w); }
; __device__ __forceinline__ void xattn_unit(const Args& a, LAS unsigned char* lds, int b, int h, int qb, int tid, int wave, int lane) {
;     ...
; #pragma unroll
;     for (int j = 0; j < 8; ++j) {
;         if (j < 6) gload(j + 2);
;         const LAS bf16* base = (const LAS bf16*)(lds + (j & 1) * STG);
;         if (j < 4) {
; #pragma unroll
;             for (int rt = 0; rt < 4; ++rt)
; #pragma unroll
;                 for (int kk = 0; kk < 8; ++kk) S[4 * j + rt] = mfma16(*(const LAS bf16x8*)(base + (16 * rt + fr) * KS + 32 * kk + 8 * fq), qf[kk], S[4 * j + rt]);
;             if (j == 3) {
;                 float mx = -3.0e38f;
; #pragma unroll
;                 for (int i = 0; i < 16; ++i) mx = fmaxf(mx, fmaxf(fmaxf(S[i][0], S[i][1]), fmaxf(S[i][2], S[i][3])));
;                 mx = fmaxf(mx, __shfl_xor(mx, 16)); mx = fmaxf(mx, __shfl_xor(mx, 32));
; #pragma unroll
;                 for (int i = 0; i < 16; ++i)
; #pragma unroll
;                     for (int k = 0; k < 4; ++k) { S[i][k] = __builtin_amdgcn_exp2f(S[i][k] - mx); l += S[i][k]; }
;                 l += __shfl_xor(l, 16); l += __shfl_xor(l, 32);
; #pragma unroll
;                 for (int c2 = 0; c2 < 8; ++c2) pf[c2] = pack8(S[2 * c2], S[2 * c2 + 1]);
;             }
;         } else {
;             const int mt = j - 4;
; #pragma unroll
;             for (int dt = 0; dt < 16; ++dt) {
;                 const LAS bf16* vr = base + (16 * dt + fr) * VS + 4 * fq;
;                 O[dt] = mfma16(cat8(*(const LAS u32x2*)vr, *(const LAS u32x2*)(vr + 16)), pf[2 * mt], O[dt]);
;                 O[dt] = mfma16(cat8(*(const LAS u32x2*)(vr + 32), *(const LAS u32x2*)(vr + 48)), pf[2 * mt + 1], O[dt]);
;             }
;         }
;         if (j < 7) lstore(j + 1);
;         __syncthreads();
	v_mfma_f32_16x16x32_bf16 v[64:67], v[68:71], v[4:7], v[64:67]
	global_load_dwordx4 v[12:15], v205, s[6:7]
	global_load_dwordx4 v[16:19], v206, s[6:7]
	global_load_dwordx4 v[20:23], v207, s[6:7]
	global_load_dwordx4 v[24:27], v208, s[6:7]
	v_mfma_f32_16x16x32_bf16 v[52:55], v[52:55], v[0:3], v[48:51]
	v_mfma_f32_16x16x32_bf16 v[56:59], v[72:75], v[0:3], v[56:59]
	v_mfma_f32_16x16x32_bf16 v[60:63], v[76:79], v[0:3], v[60:63]
	v_mfma_f32_16x16x32_bf16 v[48:51], v[80:83], v[0:3], v[64:67]
	ds_read_b128 v[76:79], v210
	ds_read_b128 v[84:87], v210 offset:64
	ds_read_b128 v[220:223], v210 offset:128
	ds_read_b128 v[132:135], v210 offset:192
	ds_read_b128 v[124:127], v210 offset:256
	ds_read_b128 v[116:119], v210 offset:320
	ds_read_b128 v[72:75], v210 offset:384
	ds_read_b128 v[64:67], v210 offset:448
	ds_read_b128 v[88:91], v210 offset:8448
	ds_read_b128 v[176:179], v210 offset:8512
	ds_read_b128 v[228:231], v210 offset:8576
	ds_read_b128 v[140:143], v210 offset:8640
	ds_read_b128 v[128:131], v210 offset:8704
	ds_read_b128 v[108:111], v210 offset:8768
	ds_read_b128 v[80:83], v210 offset:8832
	ds_read_b128 v[68:71], v210 offset:8896
	ds_read_b128 v[92:95], v210 offset:16896
	ds_read_b128 v[180:183], v210 offset:16960
	ds_read_b128 v[232:235], v210 offset:17024
	ds_read_b128 v[148:151], v210 offset:17088
	ds_read_b128 v[96:99], v209
	s_waitcnt lgkmcnt(14)
	v_mfma_f32_16x16x32_bf16 v[184:187], v[76:79], v[156:159], 0
	s_waitcnt lgkmcnt(12)
	v_mfma_f32_16x16x32_bf16 v[188:191], v[88:91], v[156:159], 0
	ds_read_b128 v[136:139], v210 offset:17152
	ds_read_b128 v[100:103], v210 offset:17216
	ds_read_b128 v[88:91], v210 offset:17280
	ds_read_b128 v[76:79], v210 offset:17344
	ds_read_b128 v[196:199], v209 offset:64
	ds_read_b128 v[236:239], v209 offset:128
	s_waitcnt lgkmcnt(6)
	v_mfma_f32_16x16x32_bf16 v[240:243], v[96:99], v[156:159], 0
	ds_read_b128 v[152:155], v209 offset:192
	ds_read_b128 v[144:147], v209 offset:256
	ds_read_b128 v[96:99], v209 offset:320
	v_mfma_f32_16x16x32_bf16 v[192:195], v[92:95], v[156:159], 0
	v_mfma_f32_16x16x32_bf16 v[244:247], v[84:87], v[120:123], v[184:187]
	ds_read_b128 v[92:95], v209 offset:384
	ds_read_b128 v[84:87], v209 offset:448
	s_waitcnt vmcnt(7)
	ds_write_b128 v211, v[160:163] offset:36864
	s_waitcnt vmcnt(6)
	ds_write_b128 v212, v[164:167] offset:36864
	s_waitcnt vmcnt(5)
	ds_write_b128 v224, v[168:171] offset:36864
	s_waitcnt vmcnt(4)
	ds_write_b128 v225, v[172:175] offset:36864
	s_waitcnt lgkmcnt(0)
	s_barrier
	v_mfma_f32_16x16x32_bf16 v[172:175], v[196:199], v[120:123], v[240:243]
	ds_read_b128 v[164:167], v210 offset:36864
	s_nop 1
	ds_read_b128 v[240:243], v210 offset:36928
	v_cndmask_b32_e32 v211, v253, v227, vcc
	v_lshlrev_b32_e32 v211, 2, v211
	s_waitcnt lgkmcnt(1)
	v_mfma_f32_16x16x32_bf16 v[248:251], v[164:167], v[156:159], 0
	ds_read_b128 v[164:167], v210 offset:45312
	ds_read_b128 v[184:187], v210 offset:45376
	v_cmp_lt_i32_e32 vcc, v204, v226
	v_mfma_f32_16x16x32_bf16 v[160:163], v[176:179], v[120:123], v[188:191]
	s_nop 0
	v_cndmask_b32_e32 v212, v253, v204, vcc
	v_lshlrev_b32_e32 v212, 2, v212
	v_mfma_f32_16x16x32_bf16 v[168:171], v[180:183], v[120:123], v[192:195]
	s_waitcnt lgkmcnt(1)
	v_mfma_f32_16x16x32_bf16 v[188:191], v[164:167], v[156:159], 0
	ds_read_b128 v[164:167], v210 offset:53760
	ds_read_b128 v[192:195], v210 offset:53824
	s_waitcnt lgkmcnt(1)
	v_mfma_f32_16x16x32_bf16 v[196:199], v[164:167], v[156:159], 0
	ds_read_b128 v[164:167], v209 offset:36864
	ds_read_b128 v[176:179], v209 offset:36928
	s_waitcnt lgkmcnt(1)
	v_mfma_f32_16x16x32_bf16 v[180:183], v[164:167], v[156:159], 0
	v_mfma_f32_16x16x32_bf16 v[164:167], v[220:223], v[112:115], v[244:247]
	v_lshrrev_b32_e32 v220, 1, v200
	v_lshrrev_b32_e32 v221, 3, v200
	v_and_b32_e32 v200, 24, v220
	v_mfma_f32_16x16x32_bf16 v[160:163], v[228:231], v[112:115], v[160:163]
	v_or_b32_e32 v222, 0x70, v214
	v_or_b32_e32 v223, 0xf0, v214
	v_mul_lo_u32 v220, v221, s22
	v_mfma_f32_16x16x32_bf16 v[156:159], v[232:235], v[112:115], v[168:171]
	v_mfma_f32_16x16x32_bf16 v[168:171], v[236:239], v[112:115], v[172:175]
	v_mfma_f32_16x16x32_bf16 v[184:187], v[184:187], v[120:123], v[188:191]
	v_mfma_f32_16x16x32_bf16 v[188:191], v[192:195], v[120:123], v[196:199]
	v_lshrrev_b32_e32 v192, 3, v217
	v_lshrrev_b32_e32 v193, 3, v218
	v_mfma_f32_16x16x32_bf16 v[172:175], v[240:243], v[120:123], v[248:251]
	s_waitcnt lgkmcnt(0)
	v_mfma_f32_16x16x32_bf16 v[120:123], v[176:179], v[120:123], v[180:183]
	v_mul_lo_u32 v178, v193, s22
	v_or_b32_e32 v177, 0xb0, v214
	v_add3_u32 v176, 0, v220, v219
	v_mfma_f32_16x16x32_bf16 v[132:135], v[132:135], v[104:107], v[164:167]
	s_nop 2
	v_mul_lo_u32 v164, v216, s22
	v_mul_lo_u32 v165, v192, s22
	v_mfma_f32_16x16x32_bf16 v[140:143], v[140:143], v[104:107], v[160:163]
	s_nop 2
	v_add3_u32 v160, 0, v164, v219
	v_add3_u32 v161, 0, v165, v219
	v_mfma_f32_16x16x32_bf16 v[164:167], v[148:151], v[104:107], v[156:159]
	v_add3_u32 v148, 0, v178, v219
	v_add_u32_e32 v162, 0, v200
	v_mad_u32_u24 v151, v215, s22, v162
	v_mfma_f32_16x16x32_bf16 v[168:171], v[152:155], v[104:107], v[168:171]
	ds_read_b128 v[152:155], v210 offset:36992
	ds_read_b128 v[178:181], v210 offset:37056
	v_mad_u32_u24 v156, v213, s22, v162
	v_mad_u32_u24 v150, v177, s22, v162
	s_waitcnt lgkmcnt(1)
	v_mfma_f32_16x16x32_bf16 v[172:175], v[152:155], v[112:115], v[172:175]
	ds_read_b128 v[152:155], v210 offset:45440
	ds_read_b128 v[192:195], v210 offset:45504
	v_mad_u32_u24 v149, v223, s22, v162
	v_add_u32_e32 v158, 0x2000, v156
	s_waitcnt lgkmcnt(1)
; #define LAS __attribute__((address_space(3)))
; __device__ __forceinline__ f32x4 mfma16(bf16x8 a, bf16x8 b, f32x4 c) { return __builtin_amdgcn_mfma_f32_16x16x32_bf16(a, b, c, 0, 0, 0); }
; __device__ __forceinline__ void xattn_unit(const Args& a, LAS unsigned char* lds, int b, int h, int qb, int tid, int wave, int lane) {
;     ...
; #pragma unroll
;             for (int rt = 0; rt < 4; ++rt)
; #pragma unroll
;                 for (int kk = 0; kk < 8; ++kk) S[4 * j + rt] = mfma16(*(const LAS bf16x8*)(base + (16 * rt + fr) * KS + 32 * kk + 8 * fq), qf[kk], S[4 * j + rt]);
;             if (j == 3) {
;                 float mx = -3.0e38f;
; #pragma unroll
;                 for (int i = 0; i < 16; ++i) mx = fmaxf(mx, fmaxf(fmaxf(S[i][0], S[i][1]), fmaxf(S[i][2], S[i][3])));
;                 mx = fmaxf(mx, __shfl_xor(mx, 16)); mx = fmaxf(mx, __shfl_xor(mx, 32));
; #pragma unroll
;                 for (int i = 0; i < 16; ++i)
; #pragma unroll
;                     for (int k = 0; k < 4; ++k) { S[i][k] = __builtin_amdgcn_exp2f(S[i][k] - mx); l += S[i][k]; }
	v_mfma_f32_16x16x32_bf16 v[182:185], v[152:155], v[112:115], v[184:187]
	ds_read_b128 v[152:155], v210 offset:53888
	ds_read_b128 v[196:199], v210 offset:53952
	v_add_u32_e32 v159, 0x2800, v156
	v_add_u32_e32 v157, 0x3000, v156
	s_waitcnt lgkmcnt(1)
	v_mfma_f32_16x16x32_bf16 v[186:189], v[152:155], v[112:115], v[188:191]
	ds_read_b128 v[152:155], v209 offset:36992
	ds_read_b128 v[214:217], v209 offset:37056
	v_add_u32_e32 v163, 0x800, v156
	s_waitcnt lgkmcnt(1)
	v_mfma_f32_16x16x32_bf16 v[218:221], v[152:155], v[112:115], v[120:123]
	v_mad_u32_u24 v152, v222, s22, v162
	v_add_u32_e32 v162, 0x1000, v156
	v_add_u32_e32 v154, 0x4800, v156
	v_mfma_f32_16x16x32_bf16 v[228:231], v[124:127], v[28:31], v[132:135]
	v_add_u32_e32 v155, 0x5000, v156
	v_add_u32_e32 v153, 0x5800, v156
	v_mfma_f32_16x16x32_bf16 v[132:135], v[136:139], v[28:31], v[164:167]
	v_add_u32_e32 v139, 0x6800, v156
	v_lshl_add_u64 v[136:137], s[4:5], 0, v[202:203]
	v_add_u32_e32 v138, 0x9000, v156
	v_mfma_f32_16x16x32_bf16 v[112:115], v[144:147], v[28:31], v[168:171]
	v_add_u32_e32 v146, 0x7000, v156
	v_add_u32_e32 v144, 0x7800, v156
	v_add_u32_e32 v145, 0x9800, v156
	v_mfma_f32_16x16x32_bf16 v[140:143], v[128:131], v[28:31], v[140:143]
	v_add_u32_e32 v147, 0xa000, v156
	v_add_u32_e32 v164, 0x9000, v151
	v_add_u32_e32 v165, 0xb000, v156
	v_mfma_f32_16x16x32_bf16 v[120:123], v[178:181], v[104:107], v[172:175]
	v_add_u32_e32 v166, 0xb800, v156
	v_add_u32_e32 v167, 0xc000, v156
	v_add_u32_e32 v168, 0x9000, v152
	v_mfma_f32_16x16x32_bf16 v[100:103], v[100:103], v[8:11], v[132:135]
	v_add_u32_e32 v169, 0xd800, v156
	v_add_u32_e32 v170, 0xe000, v156
	v_add_u32_e32 v171, 0xe800, v156
	v_mfma_f32_16x16x32_bf16 v[96:99], v[96:99], v[8:11], v[112:115]
	s_nop 2
	ds_read_b128 v[112:115], v210 offset:37120
	ds_read_b128 v[132:135], v210 offset:37184
	v_add_u32_e32 v172, 0x9000, v150
	v_add_u32_e32 v173, 0xf800, v156
	v_mfma_f32_16x16x32_bf16 v[124:127], v[192:195], v[104:107], v[182:185]
	v_add_u32_e32 v177, 0x7000, v138
	v_add_u32_e32 v175, 0x7800, v138
	v_add_u32_e32 v174, 0x9000, v149
	v_mfma_f32_16x16x32_bf16 v[108:111], v[108:111], v[8:11], v[140:143]
	v_lshl_add_u64 v[136:137], v[136:137], 0, s[0:1]
	v_lshl_add_u64 v[136:137], v[136:137], 0, v[200:201]
	s_waitcnt lgkmcnt(1)
	v_mfma_f32_16x16x32_bf16 v[112:115], v[112:115], v[28:31], v[120:123]
	s_nop 2
	ds_read_b128 v[120:123], v210 offset:45568
	ds_read_b128 v[140:143], v210 offset:45632
	v_mfma_f32_16x16x32_bf16 v[128:131], v[196:199], v[104:107], v[186:189]
	s_waitcnt lgkmcnt(1)
	v_mfma_f32_16x16x32_bf16 v[120:123], v[120:123], v[28:31], v[124:127]
	s_nop 2
	ds_read_b128 v[124:127], v210 offset:54016
	ds_read_b128 v[178:181], v210 offset:54080
	v_mfma_f32_16x16x32_bf16 v[104:107], v[214:217], v[104:107], v[218:221]
	s_waitcnt lgkmcnt(1)
	v_mfma_f32_16x16x32_bf16 v[124:127], v[124:127], v[28:31], v[128:131]
	s_nop 2
	ds_read_b128 v[128:131], v209 offset:37120
	ds_read_b128 v[182:185], v209 offset:37184
	v_mfma_f32_16x16x32_bf16 v[116:119], v[116:119], v[8:11], v[228:231]
	s_waitcnt lgkmcnt(1)
	v_mfma_f32_16x16x32_bf16 v[28:31], v[128:131], v[28:31], v[104:107]
	s_nop 2
	v_max_f32_e32 v104, v47, v47
	v_max_f32_e32 v105, v46, v46
	v_max_f32_e32 v106, v43, v43
	v_max_f32_e32 v107, v42, v42
	v_mfma_f32_16x16x32_bf16 v[72:75], v[72:75], v[4:7], v[116:119]
	v_max_f32_e32 v104, v105, v104
	s_nop 1
	v_max_f32_e32 v116, v39, v39
	v_max_f32_e32 v117, v38, v38
	v_mfma_f32_16x16x32_bf16 v[80:83], v[80:83], v[4:7], v[108:111]
	s_nop 2
	v_max_f32_e32 v108, v35, v35
	v_max_f32_e32 v109, v34, v34
	v_mfma_f32_16x16x32_bf16 v[88:91], v[88:91], v[4:7], v[100:103]
	s_nop 2
	v_max_f32_e32 v100, v107, v106
	v_max_f32_e32 v101, v117, v116
	v_max_f32_e32 v102, v109, v108
	v_max3_f32 v103, v44, v45, v104
	v_max3_f32 v100, v40, v41, v100
	v_mfma_f32_16x16x32_bf16 v[92:95], v[92:95], v[4:7], v[96:99]
	v_max3_f32 v101, v36, v37, v101
	v_max3_f32 v102, v32, v33, v102
	v_max3_f32 v100, v103, s21, v100
	v_mfma_f32_16x16x32_bf16 v[96:99], v[132:135], v[8:11], v[112:115]
	v_max_f32_e32 v108, v55, v55
	v_max_f32_e32 v109, v54, v54
	v_max_f32_e32 v116, v62, v62
	v_max_f32_e32 v113, v59, v59
	v_max_f32_e32 v114, v58, v58
	v_max3_f32 v112, v100, v101, v102
	v_mfma_f32_16x16x32_bf16 v[100:103], v[140:143], v[8:11], v[120:123]
	v_max_f32_e32 v115, v63, v63
	v_mfma_f32_16x16x32_bf16 v[104:107], v[178:181], v[8:11], v[124:127]
	s_waitcnt lgkmcnt(0)
	v_mfma_f32_16x16x32_bf16 v[8:11], v[182:185], v[8:11], v[28:31]
	s_nop 2
	v_max_f32_e32 v28, v51, v51
	v_max_f32_e32 v29, v50, v50
	v_max_f32_e32 v30, v109, v108
	v_max_f32_e32 v31, v114, v113
	v_mfma_f32_16x16x32_bf16 v[108:111], v[64:67], v[0:3], v[72:75]
	v_max_f32_e32 v64, v116, v115
	v_max_f32_e32 v28, v29, v28
	v_max3_f32 v29, v52, v53, v30
	v_max3_f32 v30, v56, v57, v31
	v_max3_f32 v31, v60, v61, v64
	v_max3_f32 v28, v48, v49, v28
	v_max3_f32 v29, v112, v29, v30
	v_max3_f32 v116, v29, v31, v28
	ds_read_b128 v[28:31], v210 offset:37248
	ds_read_b128 v[72:75], v210 offset:37312
	v_mfma_f32_16x16x32_bf16 v[76:79], v[76:79], v[0:3], v[88:91]
	v_max_f32_e32 v117, v111, v111
	v_max_f32_e32 v118, v110, v110
	v_mfma_f32_16x16x32_bf16 v[84:87], v[84:87], v[0:3], v[92:95]
	s_waitcnt lgkmcnt(1)
	v_mfma_f32_16x16x32_bf16 v[88:91], v[28:31], v[4:7], v[96:99]
	ds_read_b128 v[28:31], v210 offset:45696
	ds_read_b128 v[92:95], v210 offset:45760
	s_waitcnt lgkmcnt(1)
	v_mfma_f32_16x16x32_bf16 v[96:99], v[28:31], v[4:7], v[100:103]
	ds_read_b128 v[28:31], v210 offset:54144
	s_nop 1
	ds_read_b128 v[100:103], v210 offset:54208
	s_waitcnt lgkmcnt(1)
	v_mfma_f32_16x16x32_bf16 v[104:107], v[28:31], v[4:7], v[104:107]
	ds_read_b128 v[28:31], v209 offset:37248
	ds_read_b128 v[112:115], v209 offset:37312
	v_mfma_f32_16x16x32_bf16 v[80:83], v[68:71], v[0:3], v[80:83]
	s_waitcnt lgkmcnt(1)
	v_mfma_f32_16x16x32_bf16 v[4:7], v[28:31], v[4:7], v[8:11]
	global_load_dwordx4 v[68:71], v205, s[6:7] offset:128
	global_load_dwordx4 v[28:31], v206, s[6:7] offset:128
	global_load_dwordx4 v[64:67], v207, s[6:7] offset:128
	v_mfma_f32_16x16x32_bf16 v[8:11], v[72:75], v[0:3], v[88:91]
	global_load_dwordx4 v[72:75], v208, s[6:7] offset:128
	s_waitcnt vmcnt(7)
	ds_write_b128 v176, v[12:15]
	s_waitcnt vmcnt(6)
	ds_write_b128 v160, v[16:19]
	s_waitcnt vmcnt(5)
	ds_write_b128 v161, v[20:23]
	s_waitcnt vmcnt(4)
	ds_write_b128 v148, v[24:27]
	s_waitcnt lgkmcnt(0)
	v_mfma_f32_16x16x32_bf16 v[88:91], v[92:95], v[0:3], v[96:99]
	s_barrier
; #define LAS __attribute__((address_space(3)))
; __device__ __forceinline__ f32x4 mfma16(bf16x8 a, bf16x8 b, f32x4 c) { return __builtin_amdgcn_mfma_f32_16x16x32_bf16(a, b, c, 0, 0, 0); }
; __device__ __forceinline__ bf16x8 pack8(f32x4 a, f32x4 b) { u32x4 w; w.x = pk2(a[0], a[1]); w.y = pk2(a[2], a[3]); w.z = pk2(b[0], b[1]); w.w = pk2(b[2], b[3]); return __builtin_bit_cast(bf16x8, w); }
; __device__ __forceinline__ void xattn_unit(const Args& a, LAS unsigned char* lds, int b, int h, int qb, int tid, int wave, int lane) {
;     ...
;                 float mx = -3.0e38f;
; #pragma unroll
;                 for (int i = 0; i < 16; ++i) mx = fmaxf(mx, fmaxf(fmaxf(S[i][0], S[i][1]), fmaxf(S[i][2], S[i][3])));
;                 mx = fmaxf(mx, __shfl_xor(mx, 16)); mx = fmaxf(mx, __shfl_xor(mx, 32));
; #pragma unroll
;                 for (int i = 0; i < 16; ++i)
; #pragma unroll
;                     for (int k = 0; k < 4; ++k) { S[i][k] = __builtin_amdgcn_exp2f(S[i][k] - mx); l += S[i][k]; }
;                 l += __shfl_xor(l, 16); l += __shfl_xor(l, 32);
; #pragma unroll
;                 for (int c2 = 0; c2 < 8; ++c2) pf[c2] = pack8(S[2 * c2], S[2 * c2 + 1]);
;             }
;         } else {
;             const int mt = j - 4;
; #pragma unroll
;             for (int dt = 0; dt < 16; ++dt) {
;                 const LAS bf16* vr = base + (16 * dt + fr) * VS + 4 * fq;
;                 O[dt] = mfma16(cat8(*(const LAS u32x2*)vr, *(const LAS u32x2*)(vr + 16)), pf[2 * mt], O[dt]);
;                 O[dt] = mfma16(cat8(*(const LAS u32x2*)(vr + 32), *(const LAS u32x2*)(vr + 48)), pf[2 * mt + 1], O[dt]);
	ds_read2_b64 v[12:15], v156 offset1:4
	ds_read2_b64 v[16:19], v163 offset0:32 offset1:36
	v_max_f32_e32 v96, v83, v83
	v_max_f32_e32 v97, v82, v82
	v_max_f32_e32 v98, v79, v79
	v_mfma_f32_16x16x32_bf16 v[92:95], v[100:103], v[0:3], v[104:107]
	v_max_f32_e32 v99, v78, v78
	v_max_f32_e32 v100, v87, v87
	v_max_f32_e32 v101, v86, v86
	v_mfma_f32_16x16x32_bf16 v[0:3], v[112:115], v[0:3], v[4:7]
	ds_read2_b64 v[20:23], v162 offset0:64 offset1:68
	ds_read2_b64 v[24:27], v151 offset1:4
	ds_read2_b64 v[112:115], v156 offset0:8 offset1:12
	v_max_f32_e32 v4, v118, v117
	v_max_f32_e32 v5, v97, v96
	v_max_f32_e32 v6, v99, v98
	v_max_f32_e32 v7, v101, v100
	v_max3_f32 v4, v108, v109, v4
	v_max3_f32 v5, v80, v81, v5
	v_max3_f32 v6, v76, v77, v6
	v_max3_f32 v7, v84, v85, v7
	v_max3_f32 v4, v116, v4, v5
	v_max3_f32 v4, v4, v6, v7
	v_max_f32_e32 v5, v11, v11
	v_max_f32_e32 v6, v10, v10
	v_max_f32_e32 v7, v91, v91
	v_max_f32_e32 v96, v90, v90
	v_max_f32_e32 v97, v95, v95
	v_max_f32_e32 v98, v94, v94
	v_max_f32_e32 v99, v3, v3
	v_max_f32_e32 v100, v2, v2
	v_max_f32_e32 v5, v6, v5
	v_max_f32_e32 v6, v96, v7
	v_max_f32_e32 v7, v98, v97
	v_max_f32_e32 v96, v100, v99
	v_max3_f32 v5, v8, v9, v5
	v_max3_f32 v6, v88, v89, v6
	v_max3_f32 v7, v92, v93, v7
	v_max3_f32 v96, v0, v1, v96
	v_max3_f32 v4, v4, v5, v6
	v_max3_f32 v4, v4, v7, v96
	ds_bpermute_b32 v5, v211, v4
	s_waitcnt lgkmcnt(0)
	v_max_f32_e32 v5, v5, v5
	v_max_f32_e32 v4, v4, v5
	ds_bpermute_b32 v5, v212, v4
	s_waitcnt lgkmcnt(0)
	v_max_f32_e32 v5, v5, v5
	v_max_f32_e32 v4, v4, v5
	v_sub_f32_e32 v5, v44, v4
	v_sub_f32_e32 v6, v45, v4
	v_sub_f32_e32 v7, v46, v4
	v_sub_f32_e32 v44, v47, v4
	v_sub_f32_e32 v40, v40, v4
	v_sub_f32_e32 v41, v41, v4
	v_sub_f32_e32 v42, v42, v4
	v_sub_f32_e32 v43, v43, v4
	v_sub_f32_e32 v36, v36, v4
	v_sub_f32_e32 v37, v37, v4
	v_sub_f32_e32 v38, v38, v4
	v_sub_f32_e32 v39, v39, v4
	v_sub_f32_e32 v32, v32, v4
	v_sub_f32_e32 v33, v33, v4
	v_sub_f32_e32 v34, v34, v4
	v_sub_f32_e32 v35, v35, v4
	v_sub_f32_e32 v45, v52, v4
	v_sub_f32_e32 v46, v53, v4
	v_sub_f32_e32 v47, v54, v4
	v_sub_f32_e32 v52, v55, v4
	v_sub_f32_e32 v53, v56, v4
	v_sub_f32_e32 v54, v57, v4
	v_sub_f32_e32 v55, v58, v4
	v_sub_f32_e32 v56, v59, v4
	v_sub_f32_e32 v57, v60, v4
	v_sub_f32_e32 v58, v61, v4
	v_sub_f32_e32 v59, v62, v4
	v_sub_f32_e32 v60, v63, v4
	v_sub_f32_e32 v48, v48, v4
	v_sub_f32_e32 v49, v49, v4
	v_sub_f32_e32 v50, v50, v4
	v_sub_f32_e32 v51, v51, v4
	v_sub_f32_e32 v61, v108, v4
	v_sub_f32_e32 v62, v109, v4
	v_sub_f32_e32 v63, v110, v4
	v_sub_f32_e32 v96, v111, v4
	v_sub_f32_e32 v80, v80, v4
	v_sub_f32_e32 v81, v81, v4
	v_sub_f32_e32 v82, v82, v4
	v_sub_f32_e32 v83, v83, v4
	v_sub_f32_e32 v76, v76, v4
	v_sub_f32_e32 v77, v77, v4
	v_sub_f32_e32 v78, v78, v4
	v_sub_f32_e32 v79, v79, v4
	v_sub_f32_e32 v84, v84, v4
	v_sub_f32_e32 v85, v85, v4
	v_sub_f32_e32 v86, v86, v4
	v_sub_f32_e32 v87, v87, v4
	v_sub_f32_e32 v8, v8, v4
	v_sub_f32_e32 v9, v9, v4
	v_sub_f32_e32 v10, v10, v4
	v_sub_f32_e32 v11, v11, v4
	v_sub_f32_e32 v88, v88, v4
	v_sub_f32_e32 v89, v89, v4
	v_sub_f32_e32 v90, v90, v4
	v_sub_f32_e32 v91, v91, v4
	v_sub_f32_e32 v92, v92, v4
	v_sub_f32_e32 v93, v93, v4
	v_sub_f32_e32 v94, v94, v4
	v_sub_f32_e32 v95, v95, v4
	v_sub_f32_e32 v0, v0, v4
	v_sub_f32_e32 v1, v1, v4
	v_sub_f32_e32 v2, v2, v4
	v_sub_f32_e32 v3, v3, v4
	v_exp_f32_e32 v4, v5
	v_exp_f32_e32 v97, v6
	v_exp_f32_e32 v98, v7
	v_exp_f32_e32 v99, v44
	v_exp_f32_e32 v100, v40
	v_exp_f32_e32 v189, v52
	v_add_f32_e32 v52, 0, v4
	v_exp_f32_e32 v101, v41
	v_add_f32_e32 v52, v97, v52
	v_exp_f32_e32 v102, v42
	v_add_f32_e32 v52, v98, v52
	v_exp_f32_e32 v103, v43
	v_add_f32_e32 v52, v99, v52
	v_exp_f32_e32 v104, v36
	v_add_f32_e32 v52, v100, v52
	v_exp_f32_e32 v105, v37
	v_add_f32_e32 v52, v101, v52
	v_exp_f32_e32 v106, v38
	v_exp_f32_e32 v120, v39
	v_add_f32_e32 v52, v102, v52
	v_add_f32_e32 v52, v103, v52
	v_add_f32_e32 v52, v104, v52
	v_add_f32_e32 v52, v105, v52
	v_exp_f32_e32 v190, v53
	v_exp_f32_e32 v191, v54
	v_exp_f32_e32 v192, v55
	v_exp_f32_e32 v193, v56
	v_exp_f32_e32 v194, v57
	v_exp_f32_e32 v195, v58
	v_exp_f32_e32 v196, v59
	v_exp_f32_e32 v197, v60
	v_exp_f32_e32 v203, v61
	v_exp_f32_e32 v209, v62
	v_exp_f32_e32 v210, v63
	v_exp_f32_e32 v213, v96
	v_exp_f32_e32 v214, v80
	v_exp_f32_e32 v215, v81
	v_exp_f32_e32 v216, v82
	v_exp_f32_e32 v217, v83
	v_exp_f32_e32 v218, v76
	v_exp_f32_e32 v219, v77
	v_exp_f32_e32 v220, v78
	v_exp_f32_e32 v221, v79
	v_exp_f32_e32 v222, v84
	v_exp_f32_e32 v223, v85
	v_exp_f32_e32 v224, v86
	v_exp_f32_e32 v225, v87
	v_exp_f32_e32 v232, v88
	v_exp_f32_e32 v233, v89
	v_exp_f32_e32 v234, v90
	v_exp_f32_e32 v235, v91
	v_exp_f32_e32 v236, v92
	v_exp_f32_e32 v237, v93
	v_exp_f32_e32 v238, v94
	v_exp_f32_e32 v239, v95
	v_cvt_pk_bf16_f32 v36, v4, v97
	v_cvt_pk_bf16_f32 v37, v98, v99
	v_cvt_pk_bf16_f32 v38, v100, v101
	v_cvt_pk_bf16_f32 v39, v102, v103
	v_cvt_pk_bf16_f32 v40, v104, v105
	v_cvt_pk_bf16_f32 v41, v106, v120
	v_add_f32_e32 v121, v106, v52
	ds_read2_b64 v[52:55], v158 offset0:128 offset1:132
	ds_read2_b64 v[56:59], v159 offset0:160 offset1:164
	ds_read2_b64 v[60:63], v157 offset0:192 offset1:196
	ds_read2_b64 v[76:79], v152 offset1:4
	ds_read2_b64 v[80:83], v154 offset1:4
	ds_read2_b64 v[84:87], v155 offset0:32 offset1:36
	ds_read2_b64 v[88:91], v153 offset0:64 offset1:68
	ds_read2_b64 v[92:95], v150 offset1:4
	ds_read2_b64 v[96:99], v139 offset0:128 offset1:132
	ds_read2_b64 v[100:103], v146 offset0:160 offset1:164
	ds_read2_b64 v[104:107], v144 offset0:192 offset1:196
	ds_read2_b64 v[108:111], v149 offset1:4
	v_exp_f32_e32 v182, v32
	v_exp_f32_e32 v183, v33
	v_exp_f32_e32 v184, v34
	v_exp_f32_e32 v185, v35
	v_mfma_f32_16x16x32_bf16 v[12:15], v[12:15], v[36:39], 0
	v_cvt_pk_bf16_f32 v42, v182, v183
	v_add_f32_e32 v244, v120, v121
	v_cvt_pk_bf16_f32 v43, v184, v185
	v_mfma_f32_16x16x32_bf16 v[16:19], v[16:19], v[36:39], 0
	v_exp_f32_e32 v186, v45
	v_exp_f32_e32 v187, v46
	v_exp_f32_e32 v188, v47
	v_mfma_f32_16x16x32_bf16 v[20:23], v[20:23], v[36:39], 0
	v_cvt_pk_bf16_f32 v46, v190, v191
	v_cvt_pk_bf16_f32 v44, v186, v187
	v_cvt_pk_bf16_f32 v45, v188, v189
	v_mfma_f32_16x16x32_bf16 v[24:27], v[24:27], v[36:39], 0
	v_cvt_pk_bf16_f32 v47, v192, v193
	v_exp_f32_e32 v198, v48
	v_exp_f32_e32 v199, v49
	s_waitcnt lgkmcnt(11)
; #define LAS __attribute__((address_space(3)))
; __device__ __forceinline__ f32x4 mfma16(bf16x8 a, bf16x8 b, f32x4 c) { return __builtin_amdgcn_mfma_f32_16x16x32_bf16(a, b, c, 0, 0, 0); }
; __device__ __forceinline__ void xattn_unit(const Args& a, LAS unsigned char* lds, int b, int h, int qb, int tid, int wave, int lane) {
;     ...
;         } else {
;             const int mt = j - 4;
; #pragma unroll
;             for (int dt = 0; dt < 16; ++dt) {
;                 const LAS bf16* vr = base + (16 * dt + fr) * VS + 4 * fq;
;                 O[dt] = mfma16(cat8(*(const LAS u32x2*)vr, *(const LAS u32x2*)(vr + 16)), pf[2 * mt], O[dt]);
;                 O[dt] = mfma16(cat8(*(const LAS u32x2*)(vr + 32), *(const LAS u32x2*)(vr + 48)), pf[2 * mt + 1], O[dt]);
;             }
;         }
;         if (j < 7) lstore(j + 1);
;         __syncthreads();
	v_mfma_f32_16x16x32_bf16 v[52:55], v[52:55], v[36:39], 0
	v_exp_f32_e32 v200, v50
	v_exp_f32_e32 v202, v51
	v_cvt_pk_bf16_f32 v48, v194, v195
	s_waitcnt lgkmcnt(10)
	v_mfma_f32_16x16x32_bf16 v[56:59], v[56:59], v[36:39], 0
	v_cvt_pk_bf16_f32 v49, v196, v197
	v_cvt_pk_bf16_f32 v50, v198, v199
	v_cvt_pk_bf16_f32 v51, v200, v202
	s_waitcnt lgkmcnt(9)
	v_mfma_f32_16x16x32_bf16 v[60:63], v[60:63], v[36:39], 0
	v_add_f32_e32 v182, v182, v244
	v_exp_f32_e32 v228, v8
	v_exp_f32_e32 v229, v9
	s_waitcnt lgkmcnt(8)
	v_mfma_f32_16x16x32_bf16 v[76:79], v[76:79], v[36:39], 0
	v_exp_f32_e32 v230, v10
	v_exp_f32_e32 v231, v11
	v_exp_f32_e32 v240, v0
	s_waitcnt lgkmcnt(7)
	v_mfma_f32_16x16x32_bf16 v[80:83], v[80:83], v[36:39], 0
	v_exp_f32_e32 v241, v1
	v_exp_f32_e32 v242, v2
	v_exp_f32_e32 v243, v3
	s_waitcnt lgkmcnt(6)
	v_mfma_f32_16x16x32_bf16 v[84:87], v[84:87], v[36:39], 0
	v_cvt_pk_bf16_f32 v32, v203, v209
	v_cvt_pk_bf16_f32 v33, v210, v213
	v_cvt_pk_bf16_f32 v34, v214, v215
	s_waitcnt lgkmcnt(5)
	v_mfma_f32_16x16x32_bf16 v[88:91], v[88:91], v[36:39], 0
	v_cvt_pk_bf16_f32 v35, v216, v217
	v_cvt_pk_bf16_f32 v8, v218, v219
	v_cvt_pk_bf16_f32 v9, v220, v221
	s_waitcnt lgkmcnt(4)
	v_mfma_f32_16x16x32_bf16 v[92:95], v[92:95], v[36:39], 0
	v_cvt_pk_bf16_f32 v10, v222, v223
	v_cvt_pk_bf16_f32 v11, v224, v225
	v_cvt_pk_bf16_f32 v4, v228, v229
	s_waitcnt lgkmcnt(3)
	v_mfma_f32_16x16x32_bf16 v[96:99], v[96:99], v[36:39], 0
	v_cvt_pk_bf16_f32 v5, v230, v231
	v_cvt_pk_bf16_f32 v6, v232, v233
	v_cvt_pk_bf16_f32 v7, v234, v235
	s_waitcnt lgkmcnt(2)
	v_mfma_f32_16x16x32_bf16 v[100:103], v[100:103], v[36:39], 0
	v_cvt_pk_bf16_f32 v0, v236, v237
	v_cvt_pk_bf16_f32 v1, v238, v239
	v_cvt_pk_bf16_f32 v2, v240, v241
	s_waitcnt lgkmcnt(1)
	v_mfma_f32_16x16x32_bf16 v[104:107], v[104:107], v[36:39], 0
	v_cvt_pk_bf16_f32 v3, v242, v243
	s_waitcnt lgkmcnt(0)
	v_mfma_f32_16x16x32_bf16 v[36:39], v[108:111], v[36:39], 0
	ds_read2_b64 v[108:111], v163 offset0:40 offset1:44
	v_mfma_f32_16x16x32_bf16 v[12:15], v[112:115], v[40:43], v[12:15]
	ds_read2_b64 v[112:115], v162 offset0:72 offset1:76
	s_waitcnt lgkmcnt(1)
	v_mfma_f32_16x16x32_bf16 v[16:19], v[108:111], v[40:43], v[16:19]
	ds_read2_b64 v[108:111], v151 offset0:8 offset1:12
	s_waitcnt lgkmcnt(1)
	v_mfma_f32_16x16x32_bf16 v[20:23], v[112:115], v[40:43], v[20:23]
	ds_read2_b64 v[112:115], v158 offset0:136 offset1:140
	s_waitcnt lgkmcnt(1)
	v_mfma_f32_16x16x32_bf16 v[24:27], v[108:111], v[40:43], v[24:27]
	ds_read2_b64 v[108:111], v159 offset0:168 offset1:172
	s_waitcnt lgkmcnt(1)
	v_mfma_f32_16x16x32_bf16 v[52:55], v[112:115], v[40:43], v[52:55]
	ds_read2_b64 v[112:115], v157 offset0:200 offset1:204
	s_waitcnt lgkmcnt(1)
	v_mfma_f32_16x16x32_bf16 v[56:59], v[108:111], v[40:43], v[56:59]
	ds_read2_b64 v[108:111], v152 offset0:8 offset1:12
	s_waitcnt lgkmcnt(1)
	v_mfma_f32_16x16x32_bf16 v[60:63], v[112:115], v[40:43], v[60:63]
	ds_read2_b64 v[112:115], v154 offset0:8 offset1:12
	ds_read2_b64 v[116:119], v155 offset0:40 offset1:44
	ds_read2_b64 v[120:123], v153 offset0:72 offset1:76
	s_waitcnt lgkmcnt(3)
	v_mfma_f32_16x16x32_bf16 v[76:79], v[108:111], v[40:43], v[76:79]
	global_load_dwordx4 v[108:111], v205, s[6:7] offset:256
	s_waitcnt lgkmcnt(2)
	v_mfma_f32_16x16x32_bf16 v[80:83], v[112:115], v[40:43], v[80:83]
	global_load_dwordx4 v[112:115], v206, s[6:7] offset:256
	global_load_dwordx4 v[124:127], v207, s[6:7] offset:256
	ds_read2_b64 v[128:131], v150 offset0:8 offset1:12
	s_waitcnt lgkmcnt(2)
	v_mfma_f32_16x16x32_bf16 v[84:87], v[116:119], v[40:43], v[84:87]
	global_load_dwordx4 v[116:119], v208, s[6:7] offset:256
	ds_read2_b64 v[132:135], v139 offset0:136 offset1:140
	ds_read2_b64 v[140:143], v146 offset0:168 offset1:172
	s_waitcnt lgkmcnt(3)
	v_mfma_f32_16x16x32_bf16 v[88:91], v[120:123], v[40:43], v[88:91]
	ds_read2_b64 v[120:123], v144 offset0:200 offset1:204
	ds_read2_b64 v[178:181], v149 offset0:8 offset1:12
	s_waitcnt vmcnt(7)
	ds_write_b128 v176, v[68:71] offset:36864
	s_waitcnt vmcnt(6)
	ds_write_b128 v160, v[28:31] offset:36864
	s_waitcnt vmcnt(5)
	ds_write_b128 v161, v[64:67] offset:36864
	s_waitcnt vmcnt(4)
	ds_write_b128 v148, v[72:75] offset:36864
	s_waitcnt lgkmcnt(0)
	s_barrier
	ds_read2_b64 v[72:75], v138 offset1:4
	v_mfma_f32_16x16x32_bf16 v[92:95], v[128:131], v[40:43], v[92:95]
	v_add_f32_e32 v128, v183, v182
	v_add_f32_e32 v128, v184, v128
	v_mfma_f32_16x16x32_bf16 v[68:71], v[132:135], v[40:43], v[96:99]
	v_mfma_f32_16x16x32_bf16 v[28:31], v[140:143], v[40:43], v[100:103]
	v_mfma_f32_16x16x32_bf16 v[64:67], v[120:123], v[40:43], v[104:107]
	v_mfma_f32_16x16x32_bf16 v[36:39], v[178:181], v[40:43], v[36:39]
	ds_read2_b64 v[40:43], v145 offset0:32 offset1:36
	v_add_f32_e32 v178, v185, v128
	v_add_f32_e32 v178, v186, v178
	s_waitcnt lgkmcnt(1)
	v_mfma_f32_16x16x32_bf16 v[12:15], v[72:75], v[44:47], v[12:15]
	ds_read2_b64 v[72:75], v147 offset0:64 offset1:68
	v_add_f32_e32 v178, v187, v178
	s_waitcnt lgkmcnt(1)
	v_mfma_f32_16x16x32_bf16 v[16:19], v[40:43], v[44:47], v[16:19]
	ds_read2_b64 v[40:43], v164 offset1:4
	s_waitcnt lgkmcnt(1)
	v_mfma_f32_16x16x32_bf16 v[20:23], v[72:75], v[44:47], v[20:23]
	ds_read2_b64 v[72:75], v165 offset0:128 offset1:132
	s_waitcnt lgkmcnt(1)
	v_mfma_f32_16x16x32_bf16 v[24:27], v[40:43], v[44:47], v[24:27]
	ds_read2_b64 v[40:43], v166 offset0:160 offset1:164
	s_waitcnt lgkmcnt(1)
	v_mfma_f32_16x16x32_bf16 v[52:55], v[72:75], v[44:47], v[52:55]
	ds_read2_b64 v[72:75], v167 offset0:192 offset1:196
	s_waitcnt lgkmcnt(1)
	v_mfma_f32_16x16x32_bf16 v[40:43], v[40:43], v[44:47], v[56:59]
	s_nop 2
	ds_read2_b64 v[56:59], v168 offset1:4
	s_waitcnt lgkmcnt(1)
; #define LAS __attribute__((address_space(3)))
; __device__ __forceinline__ f32x4 mfma16(bf16x8 a, bf16x8 b, f32x4 c) { return __builtin_amdgcn_mfma_f32_16x16x32_bf16(a, b, c, 0, 0, 0); }
; __device__ __forceinline__ bf16x8 pack8(f32x4 a, f32x4 b) { u32x4 w; w.x = pk2(a[0], a[1]); w.y = pk2(a[2], a[3]); w.z = pk2(b[0], b[1]); w.w = pk2(b[2], b[3]); return __builtin_bit_cast(bf16x8, w); }
; __device__ __forceinline__ void xattn_unit(const Args& a, LAS unsigned char* lds, int b, int h, int qb, int tid, int wave, int lane) {
;     ...
;                 l += __shfl_xor(l, 16); l += __shfl_xor(l, 32);
; #pragma unroll
;                 for (int c2 = 0; c2 < 8; ++c2) pf[c2] = pack8(S[2 * c2], S[2 * c2 + 1]);
;             }
;         } else {
;             const int mt = j - 4;
; #pragma unroll
;             for (int dt = 0; dt < 16; ++dt) {
;                 const LAS bf16* vr = base + (16 * dt + fr) * VS + 4 * fq;
;                 O[dt] = mfma16(cat8(*(const LAS u32x2*)vr, *(const LAS u32x2*)(vr + 16)), pf[2 * mt], O[dt]);
;                 O[dt] = mfma16(cat8(*(const LAS u32x2*)(vr + 32), *(const LAS u32x2*)(vr + 48)), pf[2 * mt + 1], O[dt]);
;             }
;         }
;         if (j < 7) lstore(j + 1);
;         __syncthreads();
	v_mfma_f32_16x16x32_bf16 v[60:63], v[72:75], v[44:47], v[60:63]
	ds_read2_b64 v[72:75], v169 offset1:4
	s_waitcnt lgkmcnt(1)
	v_mfma_f32_16x16x32_bf16 v[56:59], v[56:59], v[44:47], v[76:79]
	s_nop 2
	ds_read2_b64 v[76:79], v170 offset0:32 offset1:36
	s_waitcnt lgkmcnt(1)
	v_mfma_f32_16x16x32_bf16 v[72:75], v[72:75], v[44:47], v[80:83]
	s_nop 2
	ds_read2_b64 v[80:83], v171 offset0:64 offset1:68
	s_waitcnt lgkmcnt(1)
	v_mfma_f32_16x16x32_bf16 v[76:79], v[76:79], v[44:47], v[84:87]
	s_nop 2
	ds_read2_b64 v[84:87], v172 offset1:4
	s_waitcnt lgkmcnt(1)
	v_mfma_f32_16x16x32_bf16 v[80:83], v[80:83], v[44:47], v[88:91]
	s_nop 2
	ds_read2_b64 v[88:91], v173 offset0:128 offset1:132
	s_waitcnt lgkmcnt(1)
	v_mfma_f32_16x16x32_bf16 v[84:87], v[84:87], v[44:47], v[92:95]
	s_nop 2
	ds_read2_b64 v[92:95], v177 offset0:160 offset1:164
	s_waitcnt lgkmcnt(1)
	v_mfma_f32_16x16x32_bf16 v[68:71], v[88:91], v[44:47], v[68:71]
	ds_read2_b64 v[88:91], v175 offset0:192 offset1:196
	s_waitcnt lgkmcnt(1)
	v_mfma_f32_16x16x32_bf16 v[28:31], v[92:95], v[44:47], v[28:31]
	ds_read2_b64 v[92:95], v174 offset1:4
	s_waitcnt lgkmcnt(1)
	v_mfma_f32_16x16x32_bf16 v[64:67], v[88:91], v[44:47], v[64:67]
	ds_read2_b64 v[88:91], v138 offset0:8 offset1:12
	s_waitcnt lgkmcnt(1)
	v_mfma_f32_16x16x32_bf16 v[36:39], v[92:95], v[44:47], v[36:39]
	ds_read2_b64 v[44:47], v145 offset0:40 offset1:44
	s_waitcnt lgkmcnt(1)
	v_mfma_f32_16x16x32_bf16 v[12:15], v[88:91], v[48:51], v[12:15]
	ds_read2_b64 v[88:91], v147 offset0:72 offset1:76
	s_waitcnt lgkmcnt(1)
	v_mfma_f32_16x16x32_bf16 v[16:19], v[44:47], v[48:51], v[16:19]
	ds_read2_b64 v[44:47], v164 offset0:8 offset1:12
	s_waitcnt lgkmcnt(1)
	v_mfma_f32_16x16x32_bf16 v[20:23], v[88:91], v[48:51], v[20:23]
	ds_read2_b64 v[88:91], v165 offset0:136 offset1:140
	s_waitcnt lgkmcnt(1)
	v_mfma_f32_16x16x32_bf16 v[24:27], v[44:47], v[48:51], v[24:27]
	ds_read2_b64 v[44:47], v166 offset0:168 offset1:172
	s_waitcnt lgkmcnt(1)
	v_mfma_f32_16x16x32_bf16 v[52:55], v[88:91], v[48:51], v[52:55]
	ds_read2_b64 v[88:91], v167 offset0:200 offset1:204
	ds_read2_b64 v[92:95], v168 offset0:8 offset1:12
	ds_read2_b64 v[96:99], v169 offset0:8 offset1:12
	s_waitcnt lgkmcnt(3)
	v_mfma_f32_16x16x32_bf16 v[40:43], v[44:47], v[48:51], v[40:43]
	global_load_dwordx4 v[44:47], v205, s[6:7] offset:384
	s_waitcnt lgkmcnt(2)
	v_mfma_f32_16x16x32_bf16 v[60:63], v[88:91], v[48:51], v[60:63]
	global_load_dwordx4 v[88:91], v206, s[6:7] offset:384
	global_load_dwordx4 v[100:103], v207, s[6:7] offset:384
	ds_read2_b64 v[104:107], v170 offset0:40 offset1:44
	s_waitcnt lgkmcnt(2)
	v_mfma_f32_16x16x32_bf16 v[56:59], v[92:95], v[48:51], v[56:59]
	global_load_dwordx4 v[92:95], v208, s[6:7] offset:384
	ds_read2_b64 v[120:123], v171 offset0:72 offset1:76
	ds_read2_b64 v[128:131], v172 offset0:8 offset1:12
	s_waitcnt lgkmcnt(1)
	v_mfma_f32_16x16x32_bf16 v[80:83], v[120:123], v[48:51], v[80:83]
	v_add_f32_e32 v120, v188, v178
	v_add_f32_e32 v120, v189, v120
	v_add_f32_e32 v120, v190, v120
	v_mfma_f32_16x16x32_bf16 v[72:75], v[96:99], v[48:51], v[72:75]
	ds_read2_b64 v[96:99], v173 offset0:136 offset1:140
	ds_read2_b64 v[132:135], v177 offset0:168 offset1:172
	ds_read2_b64 v[140:143], v175 offset0:200 offset1:204
	v_add_f32_e32 v120, v191, v120
	v_add_f32_e32 v120, v192, v120
	v_add_f32_e32 v120, v193, v120
	v_mfma_f32_16x16x32_bf16 v[76:79], v[104:107], v[48:51], v[76:79]
	ds_read2_b64 v[104:107], v174 offset0:8 offset1:12
	s_waitcnt vmcnt(7)
	ds_write_b128 v176, v[108:111]
	s_waitcnt vmcnt(6)
	ds_write_b128 v160, v[112:115]
	s_waitcnt vmcnt(5)
	ds_write_b128 v161, v[124:127]
	s_waitcnt vmcnt(4)
	ds_write_b128 v148, v[116:119]
	s_waitcnt lgkmcnt(0)
	v_mfma_f32_16x16x32_bf16 v[68:71], v[96:99], v[48:51], v[68:71]
	v_add_f32_e32 v96, v194, v120
	v_add_f32_e32 v96, v195, v96
	v_add_f32_e32 v96, v196, v96
	v_add_f32_e32 v96, v197, v96
	v_add_f32_e32 v96, v198, v96
	v_add_f32_e32 v96, v199, v96
	v_add_f32_e32 v96, v200, v96
	v_add_f32_e32 v96, v202, v96
	v_add_f32_e32 v96, v203, v96
	v_mfma_f32_16x16x32_bf16 v[84:87], v[128:131], v[48:51], v[84:87]
	s_barrier
	v_mfma_f32_16x16x32_bf16 v[28:31], v[132:135], v[48:51], v[28:31]
	v_mfma_f32_16x16x32_bf16 v[64:67], v[140:143], v[48:51], v[64:67]
	v_mfma_f32_16x16x32_bf16 v[36:39], v[104:107], v[48:51], v[36:39]
	v_add_f32_e32 v48, v209, v96
	v_add_f32_e32 v48, v210, v48
	v_add_f32_e32 v48, v213, v48
	v_add_f32_e32 v48, v214, v48
	v_add_f32_e32 v48, v215, v48
	v_add_f32_e32 v48, v216, v48
	v_add_f32_e32 v48, v217, v48
	v_add_f32_e32 v48, v218, v48
	v_add_f32_e32 v48, v219, v48
	v_add_f32_e32 v48, v220, v48
	v_add_f32_e32 v48, v221, v48
	v_add_f32_e32 v48, v222, v48
	v_add_f32_e32 v48, v223, v48
	v_add_f32_e32 v48, v224, v48
	v_add_f32_e32 v48, v225, v48
	v_add_f32_e32 v48, v228, v48
	v_add_f32_e32 v48, v229, v48
	v_add_f32_e32 v48, v230, v48
	v_add_f32_e32 v48, v231, v48
	v_add_f32_e32 v48, v232, v48
	v_add_f32_e32 v48, v233, v48
	v_add_f32_e32 v48, v234, v48
	v_add_f32_e32 v48, v235, v48
	v_add_f32_e32 v48, v236, v48
	v_add_f32_e32 v48, v237, v48
	v_add_f32_e32 v48, v238, v48
	v_add_f32_e32 v48, v239, v48
	v_add_f32_e32 v48, v240, v48
	v_add_f32_e32 v48, v241, v48
	v_add_f32_e32 v48, v242, v48
	v_add_f32_e32 v48, v243, v48
	s_nop 0
	s_waitcnt lgkmcnt(0)
	v_mov_b32_e32 v49, v48
	s_nop 1
	v_permlane16_swap_b32_e32 v48, v49
	v_add_f32_e32 v48, v48, v49
	s_nop 0
	s_waitcnt lgkmcnt(0)
; #define LAS __attribute__((address_space(3)))
; __device__ __forceinline__ f32x4 mfma16(bf16x8 a, bf16x8 b, f32x4 c) { return __builtin_amdgcn_mfma_f32_16x16x32_bf16(a, b, c, 0, 0, 0); }
; __device__ __forceinline__ void xattn_unit(const Args& a, LAS unsigned char* lds, int b, int h, int qb, int tid, int wave, int lane) {
;     ...
; #pragma unroll
;             for (int dt = 0; dt < 16; ++dt) {
;                 const LAS bf16* vr = base + (16 * dt + fr) * VS + 4 * fq;
;                 O[dt] = mfma16(cat8(*(const LAS u32x2*)vr, *(const LAS u32x2*)(vr + 16)), pf[2 * mt], O[dt]);
;                 O[dt] = mfma16(cat8(*(const LAS u32x2*)(vr + 32), *(const LAS u32x2*)(vr + 48)), pf[2 * mt + 1], O[dt]);
;             }
;         }
;         if (j < 7) lstore(j + 1);
;         __syncthreads();
;     }
;     const float il = 1.f / l;
	v_mov_b32_e32 v49, v48
	s_nop 1
	v_permlane32_swap_b32_e32 v48, v49
	v_add_f32_e32 v48, v48, v49
	v_div_scale_f32 v49, s[6:7], v48, v48, 1.0
	v_rcp_f32_e32 v51, v49
	v_div_scale_f32 v50, vcc, 1.0, v48, 1.0
	v_fma_f32 v96, -v49, v51, 1.0
	v_fmac_f32_e32 v51, v96, v51
	v_mul_f32_e32 v96, v50, v51
	v_fma_f32 v97, -v49, v96, v50
	v_fmac_f32_e32 v96, v97, v51
	v_fma_f32 v49, -v49, v96, v50
	v_div_fmas_f32 v49, v49, v51, v96
	v_div_fixup_f32 v120, v49, v48, 1.0
	ds_read2_b64 v[108:111], v156 offset1:4
	ds_read2_b64 v[112:115], v163 offset0:32 offset1:36
	ds_read2_b64 v[116:119], v162 offset0:64 offset1:68
	ds_read2_b64 v[122:125], v151 offset1:4
	ds_read2_b64 v[126:129], v158 offset0:128 offset1:132
	ds_read2_b64 v[178:181], v159 offset0:160 offset1:164
	ds_read2_b64 v[182:185], v157 offset0:192 offset1:196
	ds_read2_b64 v[186:189], v152 offset1:4
	s_nop 0
	s_nop 0
	s_waitcnt lgkmcnt(7)
	v_mfma_f32_16x16x32_bf16 v[12:15], v[108:111], v[32:35], v[12:15]
	ds_read2_b64 v[190:193], v154 offset1:4
	s_nop 0
	s_waitcnt lgkmcnt(7)
	v_mfma_f32_16x16x32_bf16 v[16:19], v[112:115], v[32:35], v[16:19]
	ds_read2_b64 v[108:111], v155 offset0:32 offset1:36
	s_nop 0
	s_waitcnt lgkmcnt(7)
	v_mfma_f32_16x16x32_bf16 v[20:23], v[116:119], v[32:35], v[20:23]
	ds_read2_b64 v[112:115], v153 offset0:64 offset1:68
	s_nop 0
	s_waitcnt lgkmcnt(7)
	v_mfma_f32_16x16x32_bf16 v[24:27], v[122:125], v[32:35], v[24:27]
	ds_read2_b64 v[116:119], v150 offset1:4
	s_nop 0
	s_waitcnt lgkmcnt(7)
	v_mfma_f32_16x16x32_bf16 v[48:51], v[126:129], v[32:35], v[52:55]
	ds_read2_b64 v[122:125], v139 offset0:128 offset1:132
	s_nop 2
	s_nop 0
	s_waitcnt lgkmcnt(7)
	v_mfma_f32_16x16x32_bf16 v[40:43], v[178:181], v[32:35], v[40:43]
	ds_read2_b64 v[126:129], v146 offset0:160 offset1:164
	s_nop 0
	s_waitcnt lgkmcnt(7)
	v_mfma_f32_16x16x32_bf16 v[52:55], v[182:185], v[32:35], v[60:63]
	ds_read2_b64 v[178:181], v144 offset0:192 offset1:196
	s_nop 2
	s_nop 0
	s_waitcnt lgkmcnt(7)
	v_mfma_f32_16x16x32_bf16 v[56:59], v[186:189], v[32:35], v[56:59]
	ds_read2_b64 v[182:185], v149 offset1:4
	s_nop 0
	s_waitcnt lgkmcnt(7)
	v_mfma_f32_16x16x32_bf16 v[60:63], v[190:193], v[32:35], v[72:75]
	ds_read2_b64 v[186:189], v156 offset0:8 offset1:12
	s_nop 2
	s_nop 0
	s_waitcnt lgkmcnt(7)
	v_mfma_f32_16x16x32_bf16 v[76:79], v[108:111], v[32:35], v[76:79]
	ds_read2_b64 v[190:193], v163 offset0:40 offset1:44
	s_nop 0
	s_waitcnt lgkmcnt(7)
	v_mfma_f32_16x16x32_bf16 v[72:75], v[112:115], v[32:35], v[80:83]
	ds_read2_b64 v[108:111], v162 offset0:72 offset1:76
	s_nop 2
	s_nop 0
	s_waitcnt lgkmcnt(7)
	v_mfma_f32_16x16x32_bf16 v[84:87], v[116:119], v[32:35], v[84:87]
	ds_read2_b64 v[112:115], v151 offset0:8 offset1:12
	s_nop 0
	s_waitcnt lgkmcnt(7)
	v_mfma_f32_16x16x32_bf16 v[68:71], v[122:125], v[32:35], v[68:71]
	ds_read2_b64 v[116:119], v158 offset0:136 offset1:140
	s_nop 0
	s_waitcnt lgkmcnt(7)
	v_mfma_f32_16x16x32_bf16 v[28:31], v[126:129], v[32:35], v[28:31]
	ds_read2_b64 v[122:125], v159 offset0:168 offset1:172
	s_nop 0
	s_waitcnt lgkmcnt(7)
	v_mfma_f32_16x16x32_bf16 v[64:67], v[178:181], v[32:35], v[64:67]
	ds_read2_b64 v[126:129], v157 offset0:200 offset1:204
	s_nop 0
	s_waitcnt lgkmcnt(7)
	v_mfma_f32_16x16x32_bf16 v[32:35], v[182:185], v[32:35], v[36:39]
	ds_read2_b64 v[178:181], v152 offset0:8 offset1:12
	s_nop 2
	s_nop 0
	s_waitcnt lgkmcnt(7)
	v_mfma_f32_16x16x32_bf16 v[12:15], v[186:189], v[8:11], v[12:15]
	ds_read2_b64 v[182:185], v154 offset0:8 offset1:12
	s_nop 0
	s_waitcnt lgkmcnt(7)
	v_mfma_f32_16x16x32_bf16 v[16:19], v[190:193], v[8:11], v[16:19]
	ds_read2_b64 v[186:189], v155 offset0:40 offset1:44
	s_nop 0
	s_waitcnt lgkmcnt(7)
	v_mfma_f32_16x16x32_bf16 v[20:23], v[108:111], v[8:11], v[20:23]
	ds_read2_b64 v[190:193], v153 offset0:72 offset1:76
	s_nop 0
	s_waitcnt lgkmcnt(7)
	v_mfma_f32_16x16x32_bf16 v[24:27], v[112:115], v[8:11], v[24:27]
	ds_read2_b64 v[108:111], v150 offset0:8 offset1:12
	s_nop 0
	s_waitcnt lgkmcnt(7)
	v_mfma_f32_16x16x32_bf16 v[48:51], v[116:119], v[8:11], v[48:51]
	ds_read2_b64 v[112:115], v139 offset0:136 offset1:140
	s_nop 0
	s_waitcnt lgkmcnt(7)
	v_mfma_f32_16x16x32_bf16 v[36:39], v[122:125], v[8:11], v[40:43]
	s_nop 2
	s_nop 0
	s_waitcnt lgkmcnt(6)
	v_mfma_f32_16x16x32_bf16 v[52:55], v[126:129], v[8:11], v[52:55]
	s_nop 0
	s_waitcnt lgkmcnt(5)
	v_mfma_f32_16x16x32_bf16 v[40:43], v[178:181], v[8:11], v[56:59]
	s_nop 2
	s_nop 0
	s_waitcnt lgkmcnt(4)
	v_mfma_f32_16x16x32_bf16 v[60:63], v[182:185], v[8:11], v[60:63]
	s_nop 0
	s_waitcnt lgkmcnt(3)
	v_mfma_f32_16x16x32_bf16 v[56:59], v[186:189], v[8:11], v[76:79]
	s_nop 2
	s_nop 0
	s_waitcnt lgkmcnt(2)
	v_mfma_f32_16x16x32_bf16 v[72:75], v[190:193], v[8:11], v[72:75]
	s_nop 0
	ds_read2_b64 v[96:99], v146 offset0:168 offset1:172
	s_waitcnt lgkmcnt(2)
	v_mfma_f32_16x16x32_bf16 v[76:79], v[108:111], v[8:11], v[84:87]
	s_nop 2
	ds_read2_b64 v[84:87], v144 offset0:200 offset1:204
	ds_read2_b64 v[104:107], v149 offset0:8 offset1:12
	s_waitcnt vmcnt(3)
	ds_write_b128 v176, v[44:47] offset:36864
	s_waitcnt vmcnt(2)
	ds_write_b128 v160, v[88:91] offset:36864
	s_waitcnt vmcnt(1)
	ds_write_b128 v161, v[100:103] offset:36864
	s_waitcnt vmcnt(0)
	ds_write_b128 v148, v[92:95] offset:36864
	s_waitcnt lgkmcnt(7)
	v_mfma_f32_16x16x32_bf16 v[44:47], v[112:115], v[8:11], v[68:71]
	s_waitcnt lgkmcnt(0)
	s_barrier
; #define LAS __attribute__((address_space(3)))
; #define GAS __attribute__((address_space(1)))
; __device__ __forceinline__ unsigned pk2(float lo, float hi) { f32x2_t v = {lo, hi}; bf16x2_t b = __builtin_convertvector(v, bf16x2_t); return __builtin_bit_cast(unsigned, b); }
; __device__ __forceinline__ f32x4 mfma16(bf16x8 a, bf16x8 b, f32x4 c) { return __builtin_amdgcn_mfma_f32_16x16x32_bf16(a, b, c, 0, 0, 0); }
; __device__ __forceinline__ void xattn_unit(const Args& a, LAS unsigned char* lds, int b, int h, int qb, int tid, int wave, int lane) {
;     ...
; #pragma unroll
;             for (int dt = 0; dt < 16; ++dt) {
;                 const LAS bf16* vr = base + (16 * dt + fr) * VS + 4 * fq;
;                 O[dt] = mfma16(cat8(*(const LAS u32x2*)vr, *(const LAS u32x2*)(vr + 16)), pf[2 * mt], O[dt]);
;                 O[dt] = mfma16(cat8(*(const LAS u32x2*)(vr + 32), *(const LAS u32x2*)(vr + 48)), pf[2 * mt + 1], O[dt]);
;             }
;         }
;         if (j < 7) lstore(j + 1);
;         __syncthreads();
;     }
;     const float il = 1.f / l;
; #pragma unroll
;     for (int dt = 0; dt < 16; ++dt) { u32x2 w; w.x = pk2(O[dt][0] * il, O[dt][1] * il); w.y = pk2(O[dt][2] * il, O[dt][3] * il);
;         *(GAS u32x2*)(XO + qrow * DM + h * 256 + 16 * dt + 4 * fq) = w; }
	v_mfma_f32_16x16x32_bf16 v[28:31], v[96:99], v[8:11], v[28:31]
	ds_read2_b64 v[108:111], v138 offset1:4
	ds_read2_b64 v[112:115], v145 offset0:32 offset1:36
	ds_read2_b64 v[116:119], v147 offset0:64 offset1:68
	ds_read2_b64 v[122:125], v164 offset1:4
	ds_read2_b64 v[126:129], v165 offset0:128 offset1:132
	ds_read2_b64 v[178:181], v166 offset0:160 offset1:164
	ds_read2_b64 v[182:185], v167 offset0:192 offset1:196
	ds_read2_b64 v[186:189], v168 offset1:4
	s_nop 0
	v_mfma_f32_16x16x32_bf16 v[64:67], v[84:87], v[8:11], v[64:67]
	v_mfma_f32_16x16x32_bf16 v[8:11], v[104:107], v[8:11], v[32:35]
	s_nop 2
	s_nop 0
	s_waitcnt lgkmcnt(7)
	v_mfma_f32_16x16x32_bf16 v[12:15], v[108:111], v[4:7], v[12:15]
	ds_read2_b64 v[190:193], v169 offset1:4
	s_nop 0
	s_waitcnt lgkmcnt(7)
	v_mfma_f32_16x16x32_bf16 v[16:19], v[112:115], v[4:7], v[16:19]
	ds_read2_b64 v[108:111], v170 offset0:32 offset1:36
	s_nop 0
	s_waitcnt lgkmcnt(7)
	v_mfma_f32_16x16x32_bf16 v[20:23], v[116:119], v[4:7], v[20:23]
	ds_read2_b64 v[112:115], v171 offset0:64 offset1:68
	s_nop 0
	s_waitcnt lgkmcnt(7)
	v_mfma_f32_16x16x32_bf16 v[24:27], v[122:125], v[4:7], v[24:27]
	ds_read2_b64 v[116:119], v172 offset1:4
	s_nop 0
	s_waitcnt lgkmcnt(7)
	v_mfma_f32_16x16x32_bf16 v[48:51], v[126:129], v[4:7], v[48:51]
	ds_read2_b64 v[122:125], v173 offset0:128 offset1:132
	s_nop 0
	s_waitcnt lgkmcnt(7)
	v_mfma_f32_16x16x32_bf16 v[32:35], v[178:181], v[4:7], v[36:39]
	ds_read2_b64 v[126:129], v177 offset0:160 offset1:164
	s_nop 2
	s_nop 0
	s_waitcnt lgkmcnt(7)
	v_mfma_f32_16x16x32_bf16 v[52:55], v[182:185], v[4:7], v[52:55]
	ds_read2_b64 v[178:181], v175 offset0:192 offset1:196
	s_nop 0
	s_waitcnt lgkmcnt(7)
	v_mfma_f32_16x16x32_bf16 v[36:39], v[186:189], v[4:7], v[40:43]
	ds_read2_b64 v[182:185], v174 offset1:4
	s_nop 2
	s_nop 0
	s_waitcnt lgkmcnt(7)
	v_mfma_f32_16x16x32_bf16 v[60:63], v[190:193], v[4:7], v[60:63]
	ds_read2_b64 v[186:189], v138 offset0:8 offset1:12
	s_nop 0
	s_waitcnt lgkmcnt(7)
	v_mfma_f32_16x16x32_bf16 v[40:43], v[108:111], v[4:7], v[56:59]
	ds_read2_b64 v[190:193], v145 offset0:40 offset1:44
	s_nop 2
	s_nop 0
	s_waitcnt lgkmcnt(7)
	v_mfma_f32_16x16x32_bf16 v[68:71], v[112:115], v[4:7], v[72:75]
	ds_read2_b64 v[108:111], v147 offset0:72 offset1:76
	s_nop 2
	s_nop 0
	s_waitcnt lgkmcnt(7)
	v_mfma_f32_16x16x32_bf16 v[56:59], v[116:119], v[4:7], v[76:79]
	ds_read2_b64 v[112:115], v164 offset0:8 offset1:12
	s_nop 2
	s_nop 0
	s_waitcnt lgkmcnt(7)
	v_mfma_f32_16x16x32_bf16 v[44:47], v[122:125], v[4:7], v[44:47]
	ds_read2_b64 v[116:119], v165 offset0:136 offset1:140
	s_nop 0
	s_waitcnt lgkmcnt(7)
	v_mfma_f32_16x16x32_bf16 v[28:31], v[126:129], v[4:7], v[28:31]
	ds_read2_b64 v[122:125], v166 offset0:168 offset1:172
	s_nop 0
	s_waitcnt lgkmcnt(7)
	v_mfma_f32_16x16x32_bf16 v[64:67], v[178:181], v[4:7], v[64:67]
	ds_read2_b64 v[126:129], v167 offset0:200 offset1:204
	s_nop 0
	s_waitcnt lgkmcnt(7)
	v_mfma_f32_16x16x32_bf16 v[4:7], v[182:185], v[4:7], v[8:11]
	ds_read2_b64 v[178:181], v168 offset0:8 offset1:12
	s_nop 2
	s_nop 0
	s_waitcnt lgkmcnt(7)
	v_mfma_f32_16x16x32_bf16 v[12:15], v[186:189], v[0:3], v[12:15]
	ds_read2_b64 v[182:185], v169 offset0:8 offset1:12
	s_nop 0
	s_waitcnt lgkmcnt(7)
	v_mfma_f32_16x16x32_bf16 v[8:11], v[190:193], v[0:3], v[16:19]
	ds_read2_b64 v[186:189], v170 offset0:40 offset1:44
	s_nop 2
	s_nop 0
	s_waitcnt lgkmcnt(7)
	v_mfma_f32_16x16x32_bf16 v[20:23], v[108:111], v[0:3], v[20:23]
	ds_read2_b64 v[190:193], v171 offset0:72 offset1:76
	s_nop 0
	s_nop 0
	v_pk_mul_f32 v[8:9], v[120:121], v[8:9] op_sel_hi:[0,1]
	v_pk_mul_f32 v[10:11], v[120:121], v[10:11] op_sel_hi:[0,1]
	s_waitcnt lgkmcnt(7)
	v_mfma_f32_16x16x32_bf16 v[16:19], v[112:115], v[0:3], v[24:27]
	ds_read2_b64 v[108:111], v172 offset0:8 offset1:12
	s_nop 2
	s_nop 0
	s_waitcnt lgkmcnt(7)
	v_mfma_f32_16x16x32_bf16 v[48:51], v[116:119], v[0:3], v[48:51]
	ds_read2_b64 v[112:115], v173 offset0:136 offset1:140
	s_nop 0
	s_nop 0
	v_pk_mul_f32 v[16:17], v[120:121], v[16:17] op_sel_hi:[0,1]
	v_pk_mul_f32 v[18:19], v[120:121], v[18:19] op_sel_hi:[0,1]
	s_waitcnt lgkmcnt(7)
	v_mfma_f32_16x16x32_bf16 v[24:27], v[122:125], v[0:3], v[32:35]
	ds_read2_b64 v[116:119], v177 offset0:168 offset1:172
	s_nop 2
	s_nop 0
	s_waitcnt lgkmcnt(7)
	v_mfma_f32_16x16x32_bf16 v[52:55], v[126:129], v[0:3], v[52:55]
	ds_read2_b64 v[122:125], v175 offset0:200 offset1:204
	s_nop 0
	s_nop 0
	v_pk_mul_f32 v[24:25], v[120:121], v[24:25] op_sel_hi:[0,1]
	v_pk_mul_f32 v[26:27], v[120:121], v[26:27] op_sel_hi:[0,1]
	s_waitcnt lgkmcnt(7)
	v_mfma_f32_16x16x32_bf16 v[32:35], v[178:181], v[0:3], v[36:39]
	ds_read2_b64 v[126:129], v174 offset0:8 offset1:12
	s_nop 2
	s_nop 0
	s_waitcnt lgkmcnt(7)
; #define LAS __attribute__((address_space(3)))
; #define GAS __attribute__((address_space(1)))
; __device__ __forceinline__ unsigned pk2(float lo, float hi) { f32x2_t v = {lo, hi}; bf16x2_t b = __builtin_convertvector(v, bf16x2_t); return __builtin_bit_cast(unsigned, b); }
; __device__ __forceinline__ f32x4 mfma16(bf16x8 a, bf16x8 b, f32x4 c) { return __builtin_amdgcn_mfma_f32_16x16x32_bf16(a, b, c, 0, 0, 0); }
; __device__ __forceinline__ void xattn_unit(const Args& a, LAS unsigned char* lds, int b, int h, int qb, int tid, int wave, int lane) {
;     ...
; #pragma unroll
;             for (int dt = 0; dt < 16; ++dt) {
;                 const LAS bf16* vr = base + (16 * dt + fr) * VS + 4 * fq;
;                 O[dt] = mfma16(cat8(*(const LAS u32x2*)vr, *(const LAS u32x2*)(vr + 16)), pf[2 * mt], O[dt]);
;                 O[dt] = mfma16(cat8(*(const LAS u32x2*)(vr + 32), *(const LAS u32x2*)(vr + 48)), pf[2 * mt + 1], O[dt]);
;             }
;         }
;         if (j < 7) lstore(j + 1);
;         __syncthreads();
;     }
;     const float il = 1.f / l;
; #pragma unroll
;     for (int dt = 0; dt < 16; ++dt) { u32x2 w; w.x = pk2(O[dt][0] * il, O[dt][1] * il); w.y = pk2(O[dt][2] * il, O[dt][3] * il);
;         *(GAS u32x2*)(XO + qrow * DM + h * 256 + 16 * dt + 4 * fq) = w; }
	v_mfma_f32_16x16x32_bf16 v[60:63], v[182:185], v[0:3], v[60:63]
	s_nop 0
	s_nop 0
	v_pk_mul_f32 v[32:33], v[120:121], v[32:33] op_sel_hi:[0,1]
	v_pk_mul_f32 v[34:35], v[120:121], v[34:35] op_sel_hi:[0,1]
	s_waitcnt lgkmcnt(6)
	v_mfma_f32_16x16x32_bf16 v[36:39], v[186:189], v[0:3], v[40:43]
	s_nop 2
	s_nop 0
	s_waitcnt lgkmcnt(5)
	v_mfma_f32_16x16x32_bf16 v[68:71], v[190:193], v[0:3], v[68:71]
	s_nop 0
	s_nop 0
	v_pk_mul_f32 v[36:37], v[120:121], v[36:37] op_sel_hi:[0,1]
	v_pk_mul_f32 v[38:39], v[120:121], v[38:39] op_sel_hi:[0,1]
	s_waitcnt lgkmcnt(4)
	v_mfma_f32_16x16x32_bf16 v[40:43], v[108:111], v[0:3], v[56:59]
	s_nop 2
	s_nop 0
	s_waitcnt lgkmcnt(3)
	v_mfma_f32_16x16x32_bf16 v[44:47], v[112:115], v[0:3], v[44:47]
	s_nop 0
	s_nop 0
	v_pk_mul_f32 v[40:41], v[120:121], v[40:41] op_sel_hi:[0,1]
	v_pk_mul_f32 v[42:43], v[120:121], v[42:43] op_sel_hi:[0,1]
	s_waitcnt lgkmcnt(2)
	v_mfma_f32_16x16x32_bf16 v[28:31], v[116:119], v[0:3], v[28:31]
	s_nop 0
	s_nop 0
	v_pk_mul_f32 v[44:45], v[120:121], v[44:45] op_sel_hi:[0,1]
	v_pk_mul_f32 v[46:47], v[120:121], v[46:47] op_sel_hi:[0,1]
	s_waitcnt lgkmcnt(1)
	v_mfma_f32_16x16x32_bf16 v[64:67], v[122:125], v[0:3], v[64:67]
	s_nop 1
	v_mul_f32_e64 v28, v120, v28
	v_mul_f32_e64 v29, v120, v29
	v_pk_mul_f32 v[30:31], v[120:121], v[30:31] op_sel_hi:[0,1]
	s_waitcnt lgkmcnt(0)
	v_mfma_f32_16x16x32_bf16 v[0:3], v[126:129], v[0:3], v[4:7]
	v_mul_f32_e64 v56, v120, v68
	v_mul_f32_e64 v57, v120, v69
	s_nop 0
	v_pk_mul_f32 v[4:5], v[120:121], v[12:13] op_sel_hi:[0,1]
	v_pk_mul_f32 v[6:7], v[120:121], v[14:15] op_sel_hi:[0,1]
	v_pk_mul_f32 v[12:13], v[120:121], v[20:21] op_sel_hi:[0,1]
	v_pk_mul_f32 v[14:15], v[120:121], v[22:23] op_sel_hi:[0,1]
	v_pk_mul_f32 v[20:21], v[120:121], v[48:49] op_sel_hi:[0,1]
	v_pk_mul_f32 v[22:23], v[120:121], v[50:51] op_sel_hi:[0,1]
	v_pk_mul_f32 v[48:49], v[120:121], v[52:53] op_sel_hi:[0,1]
	v_pk_mul_f32 v[50:51], v[120:121], v[54:55] op_sel_hi:[0,1]
	v_pk_mul_f32 v[52:53], v[120:121], v[60:61] op_sel_hi:[0,1]
	v_pk_mul_f32 v[54:55], v[120:121], v[62:63] op_sel_hi:[0,1]
	v_pk_mul_f32 v[58:59], v[120:121], v[70:71] op_sel_hi:[0,1]
	v_pk_mul_f32 v[60:61], v[120:121], v[64:65] op_sel_hi:[0,1]
	v_pk_mul_f32 v[62:63], v[120:121], v[66:67] op_sel_hi:[0,1]
	v_pk_mul_f32 v[0:1], v[120:121], v[0:1] op_sel_hi:[0,1]
	v_pk_mul_f32 v[2:3], v[120:121], v[2:3] op_sel_hi:[0,1]
	v_cvt_pk_bf16_f32 v4, v4, v5
	v_cvt_pk_bf16_f32 v5, v6, v7
	s_waitcnt lgkmcnt(0)
	s_barrier
	v_cvt_pk_bf16_f32 v6, v8, v9
	v_cvt_pk_bf16_f32 v7, v10, v11
	v_cvt_pk_bf16_f32 v8, v12, v13
	v_cvt_pk_bf16_f32 v9, v14, v15
	v_cvt_pk_bf16_f32 v10, v16, v17
	v_cvt_pk_bf16_f32 v11, v18, v19
	v_cvt_pk_bf16_f32 v12, v20, v21
	v_cvt_pk_bf16_f32 v13, v22, v23
	v_cvt_pk_bf16_f32 v14, v24, v25
	v_cvt_pk_bf16_f32 v15, v26, v27
	v_cvt_pk_bf16_f32 v16, v48, v49
	v_cvt_pk_bf16_f32 v17, v50, v51
	v_cvt_pk_bf16_f32 v18, v32, v33
	v_cvt_pk_bf16_f32 v19, v34, v35
	v_cvt_pk_bf16_f32 v20, v52, v53
	v_cvt_pk_bf16_f32 v21, v54, v55
	v_cvt_pk_bf16_f32 v22, v36, v37
	v_cvt_pk_bf16_f32 v23, v38, v39
	v_cvt_pk_bf16_f32 v24, v56, v57
	v_cvt_pk_bf16_f32 v25, v58, v59
	v_cvt_pk_bf16_f32 v26, v40, v41
	v_cvt_pk_bf16_f32 v27, v42, v43
	v_cvt_pk_bf16_f32 v36, v44, v45
	v_cvt_pk_bf16_f32 v37, v46, v47
	v_cvt_pk_bf16_f32 v38, v28, v29
	v_cvt_pk_bf16_f32 v39, v30, v31
	v_cvt_pk_bf16_f32 v40, v60, v61
	v_cvt_pk_bf16_f32 v41, v62, v63
	v_cvt_pk_bf16_f32 v42, v0, v1
	v_cvt_pk_bf16_f32 v43, v2, v3
	v_bfe_u32 v44, v252, 4, 1
	v_mul_u32_u24_e32 v44, 24, v44
	v_mov_b32_e32 v45, 0
	v_lshl_add_u64 v[44:45], v[136:137], 0, v[44:45]
	v_permlane16_swap_b32_e32 v4, v6
	v_permlane16_swap_b32_e32 v5, v7
	v_permlane16_swap_b32_e32 v8, v10
	v_permlane16_swap_b32_e32 v9, v11
	v_permlane16_swap_b32_e32 v12, v14
	v_permlane16_swap_b32_e32 v13, v15
	v_permlane16_swap_b32_e32 v16, v18
	v_permlane16_swap_b32_e32 v17, v19
	v_permlane16_swap_b32_e32 v20, v22
	v_permlane16_swap_b32_e32 v21, v23
	v_permlane16_swap_b32_e32 v24, v26
	v_permlane16_swap_b32_e32 v25, v27
	v_permlane16_swap_b32_e32 v36, v38
	v_permlane16_swap_b32_e32 v37, v39
	v_permlane16_swap_b32_e32 v40, v42
	v_permlane16_swap_b32_e32 v41, v43
	global_store_dwordx4 v[44:45], v[4:7], off
	global_store_dwordx4 v[44:45], v[8:11], off offset:64
	global_store_dwordx4 v[44:45], v[12:15], off offset:128
	global_store_dwordx4 v[44:45], v[16:19], off offset:192
	global_store_dwordx4 v[44:45], v[20:23], off offset:256
	global_store_dwordx4 v[44:45], v[24:27], off offset:320
	global_store_dwordx4 v[44:45], v[36:39], off offset:384
	global_store_dwordx4 v[44:45], v[40:43], off offset:448
	s_cbranch_scc0 .LBB0_1518

; #define PG8_GAS __attribute__((address_space(1)))
; __device__ __forceinline__ unsigned pk2_(float lo, float hi) { f32x2c_t v = {lo, hi}; bf16x2c_t b = __builtin_convertvector(v, bf16x2c_t); return __builtin_bit_cast(unsigned, b); }
; __device__ __forceinline__ float silu_f(float x) { return x * __builtin_amdgcn_rcpf(1.0f + __builtin_amdgcn_exp2f(-1.4426950408889634f * x)); }
;     __device__ __forceinline__ void operator()(const f32x4 (&acc)[2][2][4][2], const Unit& u, int wr, int wc, int fr, int fq) const {
;         const int row0 = u.pm * BM + wr * 64 + fr, col0 = u.pn * 128 + wc * 32 + 8 * fq;
;         float rs8[2][4];
; #pragma unroll
;         for (int ai = 0; ai < 2; ++ai)
; #pragma unroll
;             for (int m = 0; m < 4; ++m) rs8[ai][m] = row_rstd(parts, row0 + ai * HALF + m * 16, fq);
; #pragma unroll
;         for (int ai = 0; ai < 2; ++ai)
; #pragma unroll
;             for (int m = 0; m < 4; ++m) {
;                 const int r = row0 + ai * HALF + m * 16; const float s = rs8[ai][m];
;                 float o[8];
; #pragma unroll
;                 for (int n = 0; n < 2; ++n)
; #pragma unroll
;                     for (int i = 0; i < 4; ++i) o[4 * n + i] = silu_f(acc[ai][0][m][n][i] * s) * (acc[ai][1][m][n][i] * s);
;                 u32x4 w; w.x = pk2_(o[0], o[1]); w.y = pk2_(o[2], o[3]); w.z = pk2_(o[4], o[5]); w.w = pk2_(o[6], o[7]);
;                 *(PG8_GAS u32x4*)(O + (size_t)r * 2816 + col0) = w;
;             }
.LBB0_1661:
	s_lshl_b32 s8, s8, 8
	v_mov_b32_e32 v132, v252
	s_add_i32 s8, s8, s56
	s_mov_b32 s98, s56
	v_cmp_lt_i32_e32 vcc, v227, v226
	v_bfe_u32 v200, v132, 4, 2
	v_and_or_b32 v160, v132, 15, s8
	v_lshlrev_b32_e32 v132, 4, v200
	v_ashrrev_i32_e32 v161, 31, v160
	v_or_b32_e32 v156, 16, v160
	v_lshl_add_u64 v[188:189], s[16:17], 0, v[132:133]
	v_ashrrev_i32_e32 v157, 31, v156
	v_or_b32_e32 v152, 32, v160
	v_ashrrev_i32_e32 v153, 31, v152
	v_or_b32_e32 v150, 48, v160
	v_ashrrev_i32_e32 v151, 31, v150
	v_add_u32_e32 v146, 0x80, v160
	v_ashrrev_i32_e32 v147, 31, v146
	v_add_u32_e32 v144, 0x90, v160
	v_ashrrev_i32_e32 v145, 31, v144
	v_add_u32_e32 v142, 0xa0, v160
	v_add_u32_e32 v140, 0xb0, v160
	v_cndmask_b32_e32 v132, v253, v227, vcc
	v_lshlrev_b32_e32 v132, 2, v132
	v_xor_b32_e32 v145, 32, v253
	v_cmp_lt_i32_e32 vcc, v145, v226
	v_mov_b64_e32 v[196:197], s[30:31]
	v_add_f32_e32 v240, v240, v241
	v_add_f32_e32 v242, v242, v243
	v_add_f32_e32 v244, v244, v245
	v_add_f32_e32 v246, v246, v247
	v_add_f32_e32 v240, v240, v242
	v_add_f32_e32 v244, v244, v246
	v_mov_b32_e32 v242, 0x358637bd
	s_nop 0
	v_add_f32_dpp v241, v240, v240 quad_perm:[1,0,3,2] row_mask:0xf bank_mask:0xf
	v_add_f32_dpp v245, v244, v244 quad_perm:[1,0,3,2] row_mask:0xf bank_mask:0xf
	v_and_b32_e32 v243, 60, v252
	v_lshl_add_u32 v243, v249, 7, v243
	v_add_f32_dpp v240, v241, v241 quad_perm:[2,3,0,1] row_mask:0xf bank_mask:0xf
	v_add_f32_dpp v244, v245, v245 quad_perm:[2,3,0,1] row_mask:0xf bank_mask:0xf
	v_add_u32_e32 v243, 0x21000, v243
	v_and_b32_e32 v246, 15, v252
	v_fmamk_f32 v240, v240, 0x3a800000, v242
	v_fmamk_f32 v244, v244, 0x3a800000, v242
	v_add_u32_e32 v246, s98, v246
	v_rsq_f32_e32 v240, v240
	v_rsq_f32_e32 v244, v244
	v_lshlrev_b32_e32 v246, 2, v246
	v_add_u32_e32 v246, 0x21000, v246
	ds_write_b32 v243, v240
	ds_write_b32 v243, v244 offset:64
	s_waitcnt lgkmcnt(0)
	s_barrier
	ds_read_b32 v168, v246
	ds_read_b32 v172, v246 offset:64
	ds_read_b32 v164, v246 offset:128
	ds_read_b32 v162, v246 offset:192
	ds_read_b32 v158, v246 offset:512
	ds_read_b32 v154, v246 offset:576
	ds_read_b32 v148, v246 offset:640
	ds_read_b32 v132, v246 offset:704
	s_waitcnt lgkmcnt(0)
	s_lshl_b32 s8, s63, 7
	v_lshl_or_b32 v141, v200, 3, s8
	v_or_b32_e32 v166, s57, v141
	v_ashrrev_i32_e32 v167, 31, v166
	v_lshlrev_b64 v[166:167], 1, v[166:167]
	v_mov_b64_e32 v[170:171], s[14:15]
	v_mul_f32_e32 v174, 0xbfb8aa3b, v168
	v_mul_f32_e32 v175, v168, v168
	v_pk_mul_f32 v[116:117], v[124:125], v[116:117]
	v_pk_mul_f32 v[118:119], v[126:127], v[118:119]
	v_pk_mul_f32 v[124:125], v[124:125], v[174:175] op_sel_hi:[1,0]
	v_pk_mul_f32 v[126:127], v[126:127], v[174:175] op_sel_hi:[1,0]
	v_exp_f32_e32 v124, v124
	v_exp_f32_e32 v125, v125
	v_exp_f32_e32 v126, v126
	v_exp_f32_e32 v127, v127
	v_pk_add_f32 v[124:125], v[124:125], 1.0 op_sel_hi:[1,0]
	v_pk_mul_f32 v[116:117], v[116:117], v[174:175] op_sel:[0,1] op_sel_hi:[1,1]
	v_pk_add_f32 v[126:127], v[126:127], 1.0 op_sel_hi:[1,0]
	v_rcp_f32_e32 v124, v124
	v_rcp_f32_e32 v125, v125
	v_pk_mul_f32 v[118:119], v[118:119], v[174:175] op_sel:[0,1] op_sel_hi:[1,1]
	v_rcp_f32_e32 v126, v126
	v_rcp_f32_e32 v127, v127
	v_pk_mul_f32 v[116:117], v[116:117], v[124:125]
	s_nop 0
	v_pk_mul_f32 v[118:119], v[118:119], v[126:127]
	v_pk_mul_f32 v[112:113], v[120:121], v[112:113]
	v_pk_mul_f32 v[114:115], v[122:123], v[114:115]
	v_pk_mul_f32 v[120:121], v[120:121], v[174:175] op_sel_hi:[1,0]
	v_pk_mul_f32 v[122:123], v[122:123], v[174:175] op_sel_hi:[1,0]
	v_exp_f32_e32 v120, v120
	v_exp_f32_e32 v121, v121
	v_exp_f32_e32 v122, v122
	v_exp_f32_e32 v123, v123
	v_pk_add_f32 v[120:121], v[120:121], 1.0 op_sel_hi:[1,0]
	v_pk_mul_f32 v[112:113], v[112:113], v[174:175] op_sel:[0,1] op_sel_hi:[1,1]
	v_pk_add_f32 v[122:123], v[122:123], 1.0 op_sel_hi:[1,0]
	v_rcp_f32_e32 v120, v120
	v_rcp_f32_e32 v121, v121
	v_pk_mul_f32 v[114:115], v[114:115], v[174:175] op_sel:[0,1] op_sel_hi:[1,1]
	v_rcp_f32_e32 v122, v122
	v_rcp_f32_e32 v123, v123
	v_pk_mul_f32 v[112:113], v[112:113], v[120:121]
	s_nop 0
	v_pk_mul_f32 v[114:115], v[114:115], v[122:123]
	v_cvt_pk_bf16_f32 v116, v116, v117
	v_cvt_pk_bf16_f32 v117, v118, v119
	v_cvt_pk_bf16_f32 v118, v112, v113
	v_cvt_pk_bf16_f32 v119, v114, v115
	v_mad_i64_i32 v[120:121], s[8:9], v160, s62, v[170:171]
	v_lshl_add_u64 v[120:121], v[120:121], 0, v[166:167]
	global_store_dwordx4 v[120:121], v[116:119], off
	v_mul_f32_e32 v174, 0xbfb8aa3b, v172
	v_mul_f32_e32 v175, v172, v172
	v_pk_mul_f32 v[100:101], v[108:109], v[100:101]
	v_pk_mul_f32 v[102:103], v[110:111], v[102:103]
	v_pk_mul_f32 v[108:109], v[108:109], v[174:175] op_sel_hi:[1,0]
	v_pk_mul_f32 v[110:111], v[110:111], v[174:175] op_sel_hi:[1,0]
	v_exp_f32_e32 v108, v108
	v_exp_f32_e32 v109, v109
	v_exp_f32_e32 v110, v110
	v_exp_f32_e32 v111, v111
	v_pk_add_f32 v[108:109], v[108:109], 1.0 op_sel_hi:[1,0]
	v_pk_mul_f32 v[100:101], v[100:101], v[174:175] op_sel:[0,1] op_sel_hi:[1,1]
	v_pk_add_f32 v[110:111], v[110:111], 1.0 op_sel_hi:[1,0]
	v_rcp_f32_e32 v108, v108
	v_rcp_f32_e32 v109, v109
	v_pk_mul_f32 v[102:103], v[102:103], v[174:175] op_sel:[0,1] op_sel_hi:[1,1]
	v_rcp_f32_e32 v110, v110
	v_rcp_f32_e32 v111, v111
	v_pk_mul_f32 v[100:101], v[100:101], v[108:109]
	s_nop 0
	v_pk_mul_f32 v[102:103], v[102:103], v[110:111]
	v_pk_mul_f32 v[96:97], v[104:105], v[96:97]
	v_pk_mul_f32 v[98:99], v[106:107], v[98:99]
	v_pk_mul_f32 v[104:105], v[104:105], v[174:175] op_sel_hi:[1,0]
	v_pk_mul_f32 v[106:107], v[106:107], v[174:175] op_sel_hi:[1,0]
	v_exp_f32_e32 v104, v104
	v_exp_f32_e32 v105, v105
	v_exp_f32_e32 v106, v106
	v_exp_f32_e32 v107, v107
	v_pk_add_f32 v[104:105], v[104:105], 1.0 op_sel_hi:[1,0]
; #define PG8_GAS __attribute__((address_space(1)))
; __device__ __forceinline__ unsigned pk2_(float lo, float hi) { f32x2c_t v = {lo, hi}; bf16x2c_t b = __builtin_convertvector(v, bf16x2c_t); return __builtin_bit_cast(unsigned, b); }
; __device__ __forceinline__ float silu_f(float x) { return x * __builtin_amdgcn_rcpf(1.0f + __builtin_amdgcn_exp2f(-1.4426950408889634f * x)); }
;     __device__ __forceinline__ void operator()(const f32x4 (&acc)[2][2][4][2], const Unit& u, int wr, int wc, int fr, int fq) const {
;     ...
;             for (int m = 0; m < 4; ++m) {
;                 const int r = row0 + ai * HALF + m * 16; const float s = rs8[ai][m];
;                 float o[8];
; #pragma unroll
;                 for (int n = 0; n < 2; ++n)
; #pragma unroll
;                     for (int i = 0; i < 4; ++i) o[4 * n + i] = silu_f(acc[ai][0][m][n][i] * s) * (acc[ai][1][m][n][i] * s);
;                 u32x4 w; w.x = pk2_(o[0], o[1]); w.y = pk2_(o[2], o[3]); w.z = pk2_(o[4], o[5]); w.w = pk2_(o[6], o[7]);
;                 *(PG8_GAS u32x4*)(O + (size_t)r * 2816 + col0) = w;
;             }
	v_pk_mul_f32 v[96:97], v[96:97], v[174:175] op_sel:[0,1] op_sel_hi:[1,1]
	v_pk_add_f32 v[106:107], v[106:107], 1.0 op_sel_hi:[1,0]
	v_rcp_f32_e32 v104, v104
	v_rcp_f32_e32 v105, v105
	v_pk_mul_f32 v[98:99], v[98:99], v[174:175] op_sel:[0,1] op_sel_hi:[1,1]
	v_rcp_f32_e32 v106, v106
	v_rcp_f32_e32 v107, v107
	v_pk_mul_f32 v[96:97], v[96:97], v[104:105]
	s_nop 0
	v_pk_mul_f32 v[98:99], v[98:99], v[106:107]
	v_cvt_pk_bf16_f32 v100, v100, v101
	v_cvt_pk_bf16_f32 v101, v102, v103
	v_cvt_pk_bf16_f32 v102, v96, v97
	v_cvt_pk_bf16_f32 v103, v98, v99
	v_mad_i64_i32 v[104:105], s[8:9], v156, s62, v[170:171]
	v_lshl_add_u64 v[104:105], v[104:105], 0, v[166:167]
	global_store_dwordx4 v[104:105], v[100:103], off
	v_mul_f32_e32 v174, 0xbfb8aa3b, v164
	v_mul_f32_e32 v175, v164, v164
	v_pk_mul_f32 v[84:85], v[92:93], v[84:85]
	v_pk_mul_f32 v[86:87], v[94:95], v[86:87]
	v_pk_mul_f32 v[92:93], v[92:93], v[174:175] op_sel_hi:[1,0]
	v_pk_mul_f32 v[94:95], v[94:95], v[174:175] op_sel_hi:[1,0]
	v_exp_f32_e32 v92, v92
	v_exp_f32_e32 v93, v93
	v_exp_f32_e32 v94, v94
	v_exp_f32_e32 v95, v95
	v_pk_add_f32 v[92:93], v[92:93], 1.0 op_sel_hi:[1,0]
	v_pk_mul_f32 v[84:85], v[84:85], v[174:175] op_sel:[0,1] op_sel_hi:[1,1]
	v_pk_add_f32 v[94:95], v[94:95], 1.0 op_sel_hi:[1,0]
	v_rcp_f32_e32 v92, v92
	v_rcp_f32_e32 v93, v93
	v_pk_mul_f32 v[86:87], v[86:87], v[174:175] op_sel:[0,1] op_sel_hi:[1,1]
	v_rcp_f32_e32 v94, v94
	v_rcp_f32_e32 v95, v95
	v_pk_mul_f32 v[84:85], v[84:85], v[92:93]
	s_nop 0
	v_pk_mul_f32 v[86:87], v[86:87], v[94:95]
	v_pk_mul_f32 v[80:81], v[88:89], v[80:81]
	v_pk_mul_f32 v[82:83], v[90:91], v[82:83]
	v_pk_mul_f32 v[88:89], v[88:89], v[174:175] op_sel_hi:[1,0]
	v_pk_mul_f32 v[90:91], v[90:91], v[174:175] op_sel_hi:[1,0]
	v_exp_f32_e32 v88, v88
	v_exp_f32_e32 v89, v89
	v_exp_f32_e32 v90, v90
	v_exp_f32_e32 v91, v91
	v_pk_add_f32 v[88:89], v[88:89], 1.0 op_sel_hi:[1,0]
	v_pk_mul_f32 v[80:81], v[80:81], v[174:175] op_sel:[0,1] op_sel_hi:[1,1]
	v_pk_add_f32 v[90:91], v[90:91], 1.0 op_sel_hi:[1,0]
	v_rcp_f32_e32 v88, v88
	v_rcp_f32_e32 v89, v89
	v_pk_mul_f32 v[82:83], v[82:83], v[174:175] op_sel:[0,1] op_sel_hi:[1,1]
	v_rcp_f32_e32 v90, v90
	v_rcp_f32_e32 v91, v91
	v_pk_mul_f32 v[80:81], v[80:81], v[88:89]
	s_nop 0
	v_pk_mul_f32 v[82:83], v[82:83], v[90:91]
	v_cvt_pk_bf16_f32 v84, v84, v85
	v_cvt_pk_bf16_f32 v85, v86, v87
	v_cvt_pk_bf16_f32 v86, v80, v81
	v_cvt_pk_bf16_f32 v87, v82, v83
	v_mad_i64_i32 v[88:89], s[8:9], v152, s62, v[170:171]
	v_lshl_add_u64 v[88:89], v[88:89], 0, v[166:167]
	global_store_dwordx4 v[88:89], v[84:87], off
	v_mul_f32_e32 v174, 0xbfb8aa3b, v162
	v_mul_f32_e32 v175, v162, v162
	v_pk_mul_f32 v[68:69], v[76:77], v[68:69]
	v_pk_mul_f32 v[70:71], v[78:79], v[70:71]
	v_pk_mul_f32 v[76:77], v[76:77], v[174:175] op_sel_hi:[1,0]
	v_pk_mul_f32 v[78:79], v[78:79], v[174:175] op_sel_hi:[1,0]
	v_exp_f32_e32 v76, v76
	v_exp_f32_e32 v77, v77
	v_exp_f32_e32 v78, v78
	v_exp_f32_e32 v79, v79
	v_pk_add_f32 v[76:77], v[76:77], 1.0 op_sel_hi:[1,0]
	v_pk_mul_f32 v[68:69], v[68:69], v[174:175] op_sel:[0,1] op_sel_hi:[1,1]
	v_pk_add_f32 v[78:79], v[78:79], 1.0 op_sel_hi:[1,0]
	v_rcp_f32_e32 v76, v76
	v_rcp_f32_e32 v77, v77
	v_pk_mul_f32 v[70:71], v[70:71], v[174:175] op_sel:[0,1] op_sel_hi:[1,1]
	v_rcp_f32_e32 v78, v78
	v_rcp_f32_e32 v79, v79
	v_pk_mul_f32 v[68:69], v[68:69], v[76:77]
	s_nop 0
	v_pk_mul_f32 v[70:71], v[70:71], v[78:79]
	v_pk_mul_f32 v[64:65], v[72:73], v[64:65]
	v_pk_mul_f32 v[66:67], v[74:75], v[66:67]
	v_pk_mul_f32 v[72:73], v[72:73], v[174:175] op_sel_hi:[1,0]
	v_pk_mul_f32 v[74:75], v[74:75], v[174:175] op_sel_hi:[1,0]
	v_exp_f32_e32 v72, v72
	v_exp_f32_e32 v73, v73
	v_exp_f32_e32 v74, v74
	v_exp_f32_e32 v75, v75
	v_pk_add_f32 v[72:73], v[72:73], 1.0 op_sel_hi:[1,0]
	v_pk_mul_f32 v[64:65], v[64:65], v[174:175] op_sel:[0,1] op_sel_hi:[1,1]
	v_pk_add_f32 v[74:75], v[74:75], 1.0 op_sel_hi:[1,0]
	v_rcp_f32_e32 v72, v72
	v_rcp_f32_e32 v73, v73
	v_pk_mul_f32 v[66:67], v[66:67], v[174:175] op_sel:[0,1] op_sel_hi:[1,1]
	v_rcp_f32_e32 v74, v74
	v_rcp_f32_e32 v75, v75
	v_pk_mul_f32 v[64:65], v[64:65], v[72:73]
	s_nop 0
	v_pk_mul_f32 v[66:67], v[66:67], v[74:75]
	v_cvt_pk_bf16_f32 v68, v68, v69
	v_cvt_pk_bf16_f32 v69, v70, v71
	v_cvt_pk_bf16_f32 v70, v64, v65
	v_cvt_pk_bf16_f32 v71, v66, v67
	v_mad_i64_i32 v[72:73], s[8:9], v150, s62, v[170:171]
	v_lshl_add_u64 v[72:73], v[72:73], 0, v[166:167]
	global_store_dwordx4 v[72:73], v[68:71], off
	v_mul_f32_e32 v174, 0xbfb8aa3b, v158
	v_mul_f32_e32 v175, v158, v158
	v_pk_mul_f32 v[52:53], v[60:61], v[52:53]
	v_pk_mul_f32 v[54:55], v[62:63], v[54:55]
	v_pk_mul_f32 v[60:61], v[60:61], v[174:175] op_sel_hi:[1,0]
	v_pk_mul_f32 v[62:63], v[62:63], v[174:175] op_sel_hi:[1,0]
	v_exp_f32_e32 v60, v60
	v_exp_f32_e32 v61, v61
	v_exp_f32_e32 v62, v62
	v_exp_f32_e32 v63, v63
	v_pk_add_f32 v[60:61], v[60:61], 1.0 op_sel_hi:[1,0]
	v_pk_mul_f32 v[52:53], v[52:53], v[174:175] op_sel:[0,1] op_sel_hi:[1,1]
	v_pk_add_f32 v[62:63], v[62:63], 1.0 op_sel_hi:[1,0]
	v_rcp_f32_e32 v60, v60
	v_rcp_f32_e32 v61, v61
	v_pk_mul_f32 v[54:55], v[54:55], v[174:175] op_sel:[0,1] op_sel_hi:[1,1]
	v_rcp_f32_e32 v62, v62
	v_rcp_f32_e32 v63, v63
	v_pk_mul_f32 v[52:53], v[52:53], v[60:61]
	s_nop 0
	v_pk_mul_f32 v[54:55], v[54:55], v[62:63]
	v_pk_mul_f32 v[48:49], v[56:57], v[48:49]
	v_pk_mul_f32 v[50:51], v[58:59], v[50:51]
	v_pk_mul_f32 v[56:57], v[56:57], v[174:175] op_sel_hi:[1,0]
	v_pk_mul_f32 v[58:59], v[58:59], v[174:175] op_sel_hi:[1,0]
	v_exp_f32_e32 v56, v56
	v_exp_f32_e32 v57, v57
	v_exp_f32_e32 v58, v58
	v_exp_f32_e32 v59, v59
	v_pk_add_f32 v[56:57], v[56:57], 1.0 op_sel_hi:[1,0]
	v_pk_mul_f32 v[48:49], v[48:49], v[174:175] op_sel:[0,1] op_sel_hi:[1,1]
; #define PG8_GAS __attribute__((address_space(1)))
; __device__ __forceinline__ unsigned pk2_(float lo, float hi) { f32x2c_t v = {lo, hi}; bf16x2c_t b = __builtin_convertvector(v, bf16x2c_t); return __builtin_bit_cast(unsigned, b); }
; __device__ __forceinline__ float silu_f(float x) { return x * __builtin_amdgcn_rcpf(1.0f + __builtin_amdgcn_exp2f(-1.4426950408889634f * x)); }
; #define PG8_BAR __builtin_amdgcn_s_barrier()
;     __device__ __forceinline__ void operator()(const f32x4 (&acc)[2][2][4][2], const Unit& u, int wr, int wc, int fr, int fq) const {
;     ...
;             for (int m = 0; m < 4; ++m) {
;                 const int r = row0 + ai * HALF + m * 16; const float s = rs8[ai][m];
;                 float o[8];
; #pragma unroll
;                 for (int n = 0; n < 2; ++n)
; #pragma unroll
;                     for (int i = 0; i < 4; ++i) o[4 * n + i] = silu_f(acc[ai][0][m][n][i] * s) * (acc[ai][1][m][n][i] * s);
;                 u32x4 w; w.x = pk2_(o[0], o[1]); w.y = pk2_(o[2], o[3]); w.z = pk2_(o[4], o[5]); w.w = pk2_(o[6], o[7]);
;                 *(PG8_GAS u32x4*)(O + (size_t)r * 2816 + col0) = w;
;             }
; template <class Epi, class Sched, bool ALIGN_EPI = false, bool SP2 = false>
; __device__ __forceinline__ void gemm_phase(PG8_LAS unsigned char* lds, const Gemm g, const Sched& S, const Epi& E) {
;     ...
;         if constexpr (ALIGN_EPI) { if (wr == 0) PG8_BAR; }
;         if constexpr (!Epi::AFTER_DRAIN) { int t2 = threadIdx.x; asm volatile("" : "+v"(t2)); E(acc, cur, wr, wc, t2 & 15, (t2 >> 4) & 3); S.done(cur); }
;         if (!has_next) break;
	v_pk_add_f32 v[58:59], v[58:59], 1.0 op_sel_hi:[1,0]
	v_rcp_f32_e32 v56, v56
	v_rcp_f32_e32 v57, v57
	v_pk_mul_f32 v[50:51], v[50:51], v[174:175] op_sel:[0,1] op_sel_hi:[1,1]
	v_rcp_f32_e32 v58, v58
	v_rcp_f32_e32 v59, v59
	v_pk_mul_f32 v[48:49], v[48:49], v[56:57]
	s_nop 0
	v_pk_mul_f32 v[50:51], v[50:51], v[58:59]
	v_cvt_pk_bf16_f32 v52, v52, v53
	v_cvt_pk_bf16_f32 v53, v54, v55
	v_cvt_pk_bf16_f32 v54, v48, v49
	v_cvt_pk_bf16_f32 v55, v50, v51
	v_mad_i64_i32 v[56:57], s[8:9], v146, s62, v[170:171]
	v_lshl_add_u64 v[56:57], v[56:57], 0, v[166:167]
	global_store_dwordx4 v[56:57], v[52:55], off
	v_mul_f32_e32 v174, 0xbfb8aa3b, v154
	v_mul_f32_e32 v175, v154, v154
	v_pk_mul_f32 v[36:37], v[44:45], v[36:37]
	v_pk_mul_f32 v[38:39], v[46:47], v[38:39]
	v_pk_mul_f32 v[44:45], v[44:45], v[174:175] op_sel_hi:[1,0]
	v_pk_mul_f32 v[46:47], v[46:47], v[174:175] op_sel_hi:[1,0]
	v_exp_f32_e32 v44, v44
	v_exp_f32_e32 v45, v45
	v_exp_f32_e32 v46, v46
	v_exp_f32_e32 v47, v47
	v_pk_add_f32 v[44:45], v[44:45], 1.0 op_sel_hi:[1,0]
	v_pk_mul_f32 v[36:37], v[36:37], v[174:175] op_sel:[0,1] op_sel_hi:[1,1]
	v_pk_add_f32 v[46:47], v[46:47], 1.0 op_sel_hi:[1,0]
	v_rcp_f32_e32 v44, v44
	v_rcp_f32_e32 v45, v45
	v_pk_mul_f32 v[38:39], v[38:39], v[174:175] op_sel:[0,1] op_sel_hi:[1,1]
	v_rcp_f32_e32 v46, v46
	v_rcp_f32_e32 v47, v47
	v_pk_mul_f32 v[36:37], v[36:37], v[44:45]
	s_nop 0
	v_pk_mul_f32 v[38:39], v[38:39], v[46:47]
	v_pk_mul_f32 v[32:33], v[40:41], v[32:33]
	v_pk_mul_f32 v[34:35], v[42:43], v[34:35]
	v_pk_mul_f32 v[40:41], v[40:41], v[174:175] op_sel_hi:[1,0]
	v_pk_mul_f32 v[42:43], v[42:43], v[174:175] op_sel_hi:[1,0]
	v_exp_f32_e32 v40, v40
	v_exp_f32_e32 v41, v41
	v_exp_f32_e32 v42, v42
	v_exp_f32_e32 v43, v43
	v_pk_add_f32 v[40:41], v[40:41], 1.0 op_sel_hi:[1,0]
	v_pk_mul_f32 v[32:33], v[32:33], v[174:175] op_sel:[0,1] op_sel_hi:[1,1]
	v_pk_add_f32 v[42:43], v[42:43], 1.0 op_sel_hi:[1,0]
	v_rcp_f32_e32 v40, v40
	v_rcp_f32_e32 v41, v41
	v_pk_mul_f32 v[34:35], v[34:35], v[174:175] op_sel:[0,1] op_sel_hi:[1,1]
	v_rcp_f32_e32 v42, v42
	v_rcp_f32_e32 v43, v43
	v_pk_mul_f32 v[32:33], v[32:33], v[40:41]
	s_nop 0
	v_pk_mul_f32 v[34:35], v[34:35], v[42:43]
	v_cvt_pk_bf16_f32 v36, v36, v37
	v_cvt_pk_bf16_f32 v37, v38, v39
	v_cvt_pk_bf16_f32 v38, v32, v33
	v_cvt_pk_bf16_f32 v39, v34, v35
	v_mad_i64_i32 v[40:41], s[8:9], v144, s62, v[170:171]
	v_lshl_add_u64 v[40:41], v[40:41], 0, v[166:167]
	global_store_dwordx4 v[40:41], v[36:39], off
	v_mul_f32_e32 v174, 0xbfb8aa3b, v148
	v_mul_f32_e32 v175, v148, v148
	v_pk_mul_f32 v[20:21], v[28:29], v[20:21]
	v_pk_mul_f32 v[22:23], v[30:31], v[22:23]
	v_pk_mul_f32 v[28:29], v[28:29], v[174:175] op_sel_hi:[1,0]
	v_pk_mul_f32 v[30:31], v[30:31], v[174:175] op_sel_hi:[1,0]
	v_exp_f32_e32 v28, v28
	v_exp_f32_e32 v29, v29
	v_exp_f32_e32 v30, v30
	v_exp_f32_e32 v31, v31
	v_pk_add_f32 v[28:29], v[28:29], 1.0 op_sel_hi:[1,0]
	v_pk_mul_f32 v[20:21], v[20:21], v[174:175] op_sel:[0,1] op_sel_hi:[1,1]
	v_pk_add_f32 v[30:31], v[30:31], 1.0 op_sel_hi:[1,0]
	v_rcp_f32_e32 v28, v28
	v_rcp_f32_e32 v29, v29
	v_pk_mul_f32 v[22:23], v[22:23], v[174:175] op_sel:[0,1] op_sel_hi:[1,1]
	v_rcp_f32_e32 v30, v30
	v_rcp_f32_e32 v31, v31
	v_pk_mul_f32 v[20:21], v[20:21], v[28:29]
	s_nop 0
	v_pk_mul_f32 v[22:23], v[22:23], v[30:31]
	v_pk_mul_f32 v[16:17], v[24:25], v[16:17]
	v_pk_mul_f32 v[18:19], v[26:27], v[18:19]
	v_pk_mul_f32 v[24:25], v[24:25], v[174:175] op_sel_hi:[1,0]
	v_pk_mul_f32 v[26:27], v[26:27], v[174:175] op_sel_hi:[1,0]
	v_exp_f32_e32 v24, v24
	v_exp_f32_e32 v25, v25
	v_exp_f32_e32 v26, v26
	v_exp_f32_e32 v27, v27
	v_pk_add_f32 v[24:25], v[24:25], 1.0 op_sel_hi:[1,0]
	v_pk_mul_f32 v[16:17], v[16:17], v[174:175] op_sel:[0,1] op_sel_hi:[1,1]
	v_pk_add_f32 v[26:27], v[26:27], 1.0 op_sel_hi:[1,0]
	v_rcp_f32_e32 v24, v24
	v_rcp_f32_e32 v25, v25
	v_pk_mul_f32 v[18:19], v[18:19], v[174:175] op_sel:[0,1] op_sel_hi:[1,1]
	v_rcp_f32_e32 v26, v26
	v_rcp_f32_e32 v27, v27
	v_pk_mul_f32 v[16:17], v[16:17], v[24:25]
	s_nop 0
	v_pk_mul_f32 v[18:19], v[18:19], v[26:27]
	v_cvt_pk_bf16_f32 v20, v20, v21
	v_cvt_pk_bf16_f32 v21, v22, v23
	v_cvt_pk_bf16_f32 v22, v16, v17
	v_cvt_pk_bf16_f32 v23, v18, v19
	v_mad_i64_i32 v[24:25], s[8:9], v142, s62, v[170:171]
	v_lshl_add_u64 v[24:25], v[24:25], 0, v[166:167]
	global_store_dwordx4 v[24:25], v[20:23], off
	v_mul_f32_e32 v174, 0xbfb8aa3b, v132
	v_mul_f32_e32 v175, v132, v132
	v_pk_mul_f32 v[4:5], v[12:13], v[4:5]
	v_pk_mul_f32 v[6:7], v[14:15], v[6:7]
	v_pk_mul_f32 v[12:13], v[12:13], v[174:175] op_sel_hi:[1,0]
	v_pk_mul_f32 v[14:15], v[14:15], v[174:175] op_sel_hi:[1,0]
	v_exp_f32_e32 v12, v12
	v_exp_f32_e32 v13, v13
	v_exp_f32_e32 v14, v14
	v_exp_f32_e32 v15, v15
	v_pk_add_f32 v[12:13], v[12:13], 1.0 op_sel_hi:[1,0]
	v_pk_mul_f32 v[4:5], v[4:5], v[174:175] op_sel:[0,1] op_sel_hi:[1,1]
	v_pk_add_f32 v[14:15], v[14:15], 1.0 op_sel_hi:[1,0]
	v_rcp_f32_e32 v12, v12
	v_rcp_f32_e32 v13, v13
	v_pk_mul_f32 v[6:7], v[6:7], v[174:175] op_sel:[0,1] op_sel_hi:[1,1]
	v_rcp_f32_e32 v14, v14
	v_rcp_f32_e32 v15, v15
	v_pk_mul_f32 v[4:5], v[4:5], v[12:13]
	s_nop 0
	v_pk_mul_f32 v[6:7], v[6:7], v[14:15]
	v_pk_mul_f32 v[0:1], v[8:9], v[0:1]
	v_pk_mul_f32 v[2:3], v[10:11], v[2:3]
	v_pk_mul_f32 v[8:9], v[8:9], v[174:175] op_sel_hi:[1,0]
	v_pk_mul_f32 v[10:11], v[10:11], v[174:175] op_sel_hi:[1,0]
	v_exp_f32_e32 v8, v8
	v_exp_f32_e32 v9, v9
	v_exp_f32_e32 v10, v10
	v_exp_f32_e32 v11, v11
	v_pk_add_f32 v[8:9], v[8:9], 1.0 op_sel_hi:[1,0]
	v_pk_mul_f32 v[0:1], v[0:1], v[174:175] op_sel:[0,1] op_sel_hi:[1,1]
	v_pk_add_f32 v[10:11], v[10:11], 1.0 op_sel_hi:[1,0]
	v_rcp_f32_e32 v8, v8
	v_rcp_f32_e32 v9, v9
	v_pk_mul_f32 v[2:3], v[2:3], v[174:175] op_sel:[0,1] op_sel_hi:[1,1]
	v_rcp_f32_e32 v10, v10
	v_rcp_f32_e32 v11, v11
	v_pk_mul_f32 v[0:1], v[0:1], v[8:9]
	s_nop 0
	v_pk_mul_f32 v[2:3], v[2:3], v[10:11]
	v_cvt_pk_bf16_f32 v4, v4, v5
	v_cvt_pk_bf16_f32 v5, v6, v7
	v_cvt_pk_bf16_f32 v6, v0, v1
	v_cvt_pk_bf16_f32 v7, v2, v3
	v_mad_i64_i32 v[8:9], s[8:9], v140, s62, v[170:171]
	v_lshl_add_u64 v[8:9], v[8:9], 0, v[166:167]
	s_andn2_b64 vcc, exec, s[6:7]
	s_mov_b64 s[6:7], -1
	global_store_dwordx4 v[8:9], v[4:7], off
	s_cbranch_vccnz .LBB0_1654
	s_andn2_b64 vcc, exec, s[12:13]
	s_cbranch_vccnz .LBB0_1653
	s_barrier
	s_branch .LBB0_1653
